# barriers after the norm mini-phases replaced by write-through stores + counter signal; consumers check the counter on their first tile
# speedup vs baseline: 1.0569x; 1.0112x over previous
; __device__ __forceinline__ unsigned cvt_pk_bf16(float lo, float hi) { unsigned r; asm volatile("v_cvt_pk_bf16_f32 %0, %1, %2" : "=v"(r) : "v"(lo), "v"(hi)); return r; }
; __device__ __forceinline__ float bflo(unsigned w) { return __uint_as_float(w << 16); }
; __device__ __forceinline__ float bfhi(unsigned w) { return __uint_as_float(w & 0xffff0000u); }
; __device__ __forceinline__ void norm_phase(KP p, bool first, int nslab) {
;     ...
;         f32x4 v[4]; float s = 0.f;
;         if (first) { const f32x4* xr = (const f32x4*)src_row(p, m) + lane;
; #pragma unroll
;             for (int j = 0; j < 4; ++j) v[j] = __builtin_nontemporal_load(xr + 64 * j); }
;         else { const u32x2* xr = (const u32x2*)(X + (size_t)m * D) + lane;
; #pragma unroll
;             for (int j = 0; j < 4; ++j) { const u32x2 w = __builtin_nontemporal_load(xr + 64 * j); v[j] = (f32x4){bflo(w.x), bfhi(w.x), bflo(w.y), bfhi(w.y)}; } }
;         const bool fold = (!first) && m >= 64 * 256;
;         if (fold) { const f32x4* sl = (const f32x4*)(p->ws + WS_SLAB) + (size_t)(m - 64 * 256) * (D / 4) + lane;
;             for (int q = 0; q < nslab; ++q) {
; #pragma unroll
;                 for (int j = 0; j < 4; ++j) v[j] += sl[(size_t)q * 256 * (D / 4) + 64 * j]; } }
;         if (first || fold) { u32x2* xo = (u32x2*)(X + (size_t)m * D) + lane;
; #pragma unroll
;             for (int j = 0; j < 4; ++j) { u32x2 w; w.x = cvt_pk_bf16(v[j][0], v[j][1]); w.y = cvt_pk_bf16(v[j][2], v[j][3]); xo[64 * j] = w; } }
; #pragma unroll
;         for (int j = 0; j < 4; ++j) s += (v[j][0] * v[j][0] + v[j][1] * v[j][1]) + (v[j][2] * v[j][2] + v[j][3] * v[j][3]);
;         const float rinv = rsqrtf(wave_sum(s) * (1.f / D) + EPS);
.LBB0_59:
	s_waitcnt lgkmcnt(0)
	s_cmp_eq_u32 s56, 0
	s_cbranch_scc1 .Lp1_orig
	s_mov_b64 s[4:5], s[0:1]
	v_mov_b32_e32 v0, v209
	s_load_dwordx2 s[8:9], s[4:5], 0xe8
	v_and_b32_e32 v2, 63, v0
	v_readfirstlane_b32 s6, v0
	s_nop 3
	s_lshr_b32 s6, s6, 6
	s_waitcnt lgkmcnt(0)
	s_add_u32 s10, s8, 0x25c8000
	s_addc_u32 s11, s9, 0
	s_add_u32 s12, s8, 0x18c48000
	s_addc_u32 s13, s9, 0
	s_add_u32 s14, s8, 0x19068000
	s_addc_u32 s15, s9, 0
	s_cmpk_lt_u32 s2, 32
	s_cbranch_scc1 .Lnm_part2_p1
	s_cmpk_lt_u32 s2, 0xe0
	s_cbranch_scc1 .Lp1m_exit
	s_sub_i32 s16, s2, 0xe0
	s_lshl_b32 s16, s16, 3
	s_add_i32 s16, s16, s6
	s_add_i32 s18, s16, 0x4000
	s_lshl_b32 s19, s18, 2
	s_lshl_b32 s18, s18, 11
	s_add_u32 s10, s10, s18
	s_addc_u32 s11, s11, 0
	s_add_u32 s14, s14, s19
	s_addc_u32 s15, s15, 0
	v_lshlrev_b32_e32 v5, 3, v2
	v_lshlrev_b32_e32 v6, 4, v2
	global_load_dwordx2 v[18:19], v5, s[10:11]
	global_load_dwordx2 v[20:21], v5, s[10:11] offset:512
	global_load_dwordx2 v[22:23], v5, s[10:11] offset:1024
	global_load_dwordx2 v[24:25], v5, s[10:11] offset:1536
	s_lshl_b32 s18, s16, 12
	s_add_u32 s18, s8, s18
	s_addc_u32 s19, s9, 0
	s_add_u32 s18, s18, 0x1a3ac000
	s_addc_u32 s19, s19, 0
	global_load_dwordx4 v[32:35], v6, s[18:19]
	global_load_dwordx4 v[36:39], v6, s[18:19] offset:1024
	global_load_dwordx4 v[40:43], v6, s[18:19] offset:2048
	global_load_dwordx4 v[44:47], v6, s[18:19] offset:3072
	s_add_u32 s18, s18, 0x100000
	s_addc_u32 s19, s19, 0
	global_load_dwordx4 v[48:51], v6, s[18:19]
	global_load_dwordx4 v[52:55], v6, s[18:19] offset:1024
	global_load_dwordx4 v[56:59], v6, s[18:19] offset:2048
	global_load_dwordx4 v[60:63], v6, s[18:19] offset:3072
	s_add_u32 s18, s18, 0x100000
	s_addc_u32 s19, s19, 0
	global_load_dwordx4 v[64:67], v6, s[18:19]
	global_load_dwordx4 v[68:71], v6, s[18:19] offset:1024
	global_load_dwordx4 v[72:75], v6, s[18:19] offset:2048
	global_load_dwordx4 v[76:79], v6, s[18:19] offset:3072
	s_add_u32 s18, s18, 0x100000
	s_addc_u32 s19, s19, 0
	global_load_dwordx4 v[80:83], v6, s[18:19]
	global_load_dwordx4 v[84:87], v6, s[18:19] offset:1024
	global_load_dwordx4 v[88:91], v6, s[18:19] offset:2048
	global_load_dwordx4 v[92:95], v6, s[18:19] offset:3072
	s_add_u32 s18, s18, 0x100000
	s_addc_u32 s19, s19, 0
	global_load_dwordx4 v[96:99], v6, s[18:19]
	global_load_dwordx4 v[100:103], v6, s[18:19] offset:1024
	global_load_dwordx4 v[104:107], v6, s[18:19] offset:2048
	global_load_dwordx4 v[108:111], v6, s[18:19] offset:3072
	s_add_u32 s18, s18, 0x100000
	s_addc_u32 s19, s19, 0
	global_load_dwordx4 v[112:115], v6, s[18:19]
	global_load_dwordx4 v[116:119], v6, s[18:19] offset:1024
	global_load_dwordx4 v[120:123], v6, s[18:19] offset:2048
	global_load_dwordx4 v[124:127], v6, s[18:19] offset:3072
	s_add_u32 s18, s18, 0x100000
	s_addc_u32 s19, s19, 0
	global_load_dwordx4 v[128:131], v6, s[18:19]
	global_load_dwordx4 v[132:135], v6, s[18:19] offset:1024
	global_load_dwordx4 v[136:139], v6, s[18:19] offset:2048
	global_load_dwordx4 v[140:143], v6, s[18:19] offset:3072
	s_add_u32 s18, s18, 0x100000
	s_addc_u32 s19, s19, 0
	global_load_dwordx4 v[144:147], v6, s[18:19]
	global_load_dwordx4 v[148:151], v6, s[18:19] offset:1024
	global_load_dwordx4 v[152:155], v6, s[18:19] offset:2048
	global_load_dwordx4 v[156:159], v6, s[18:19] offset:3072
	s_add_u32 s18, s18, 0x100000
	s_addc_u32 s19, s19, 0
	s_waitcnt vmcnt(32)
	v_lshlrev_b32_e32 v224, 16, v18
	v_and_b32_e32 v225, 0xffff0000, v18
	v_lshlrev_b32_e32 v226, 16, v19
	v_and_b32_e32 v227, 0xffff0000, v19
	v_lshlrev_b32_e32 v228, 16, v20
	v_and_b32_e32 v229, 0xffff0000, v20
	v_lshlrev_b32_e32 v230, 16, v21
	v_and_b32_e32 v231, 0xffff0000, v21
	v_lshlrev_b32_e32 v232, 16, v22
	v_and_b32_e32 v233, 0xffff0000, v22
	v_lshlrev_b32_e32 v234, 16, v23
	v_and_b32_e32 v235, 0xffff0000, v23
	v_lshlrev_b32_e32 v236, 16, v24
	v_and_b32_e32 v237, 0xffff0000, v24
	v_lshlrev_b32_e32 v238, 16, v25
	v_and_b32_e32 v239, 0xffff0000, v25
	s_waitcnt vmcnt(28)
	v_add_f32_e32 v224, v224, v32
	v_add_f32_e32 v225, v225, v33
	v_add_f32_e32 v226, v226, v34
	v_add_f32_e32 v227, v227, v35
	v_add_f32_e32 v228, v228, v36
	v_add_f32_e32 v229, v229, v37
	v_add_f32_e32 v230, v230, v38
	v_add_f32_e32 v231, v231, v39
	v_add_f32_e32 v232, v232, v40
	v_add_f32_e32 v233, v233, v41
	v_add_f32_e32 v234, v234, v42
	v_add_f32_e32 v235, v235, v43
	v_add_f32_e32 v236, v236, v44
	v_add_f32_e32 v237, v237, v45
	v_add_f32_e32 v238, v238, v46
	v_add_f32_e32 v239, v239, v47
	s_waitcnt vmcnt(24)
	v_add_f32_e32 v224, v224, v48
	v_add_f32_e32 v225, v225, v49
	v_add_f32_e32 v226, v226, v50
	v_add_f32_e32 v227, v227, v51
	v_add_f32_e32 v228, v228, v52
	v_add_f32_e32 v229, v229, v53
	v_add_f32_e32 v230, v230, v54
	v_add_f32_e32 v231, v231, v55
	v_add_f32_e32 v232, v232, v56
	v_add_f32_e32 v233, v233, v57
	v_add_f32_e32 v234, v234, v58
	v_add_f32_e32 v235, v235, v59
	v_add_f32_e32 v236, v236, v60
	v_add_f32_e32 v237, v237, v61
	v_add_f32_e32 v238, v238, v62
	v_add_f32_e32 v239, v239, v63
	s_waitcnt vmcnt(20)
	v_add_f32_e32 v224, v224, v64
	v_add_f32_e32 v225, v225, v65
	v_add_f32_e32 v226, v226, v66
	v_add_f32_e32 v227, v227, v67
	v_add_f32_e32 v228, v228, v68
	v_add_f32_e32 v229, v229, v69
	v_add_f32_e32 v230, v230, v70
	v_add_f32_e32 v231, v231, v71
	v_add_f32_e32 v232, v232, v72
	v_add_f32_e32 v233, v233, v73
	v_add_f32_e32 v234, v234, v74
	v_add_f32_e32 v235, v235, v75
	v_add_f32_e32 v236, v236, v76
	v_add_f32_e32 v237, v237, v77
	v_add_f32_e32 v238, v238, v78
	v_add_f32_e32 v239, v239, v79
	s_waitcnt vmcnt(16)
; __device__ __forceinline__ unsigned cvt_pk_bf16(float lo, float hi) { unsigned r; asm volatile("v_cvt_pk_bf16_f32 %0, %1, %2" : "=v"(r) : "v"(lo), "v"(hi)); return r; }
; __device__ __forceinline__ void norm_phase(KP p, bool first, int nslab) {
;     ...
;         if (fold) { const f32x4* sl = (const f32x4*)(p->ws + WS_SLAB) + (size_t)(m - 64 * 256) * (D / 4) + lane;
;             for (int q = 0; q < nslab; ++q) {
; #pragma unroll
;                 for (int j = 0; j < 4; ++j) v[j] += sl[(size_t)q * 256 * (D / 4) + 64 * j]; } }
;         if (first || fold) { u32x2* xo = (u32x2*)(X + (size_t)m * D) + lane;
; #pragma unroll
;             for (int j = 0; j < 4; ++j) { u32x2 w; w.x = cvt_pk_bf16(v[j][0], v[j][1]); w.y = cvt_pk_bf16(v[j][2], v[j][3]); xo[64 * j] = w; } }
; #pragma unroll
;         for (int j = 0; j < 4; ++j) s += (v[j][0] * v[j][0] + v[j][1] * v[j][1]) + (v[j][2] * v[j][2] + v[j][3] * v[j][3]);
;         const float rinv = rsqrtf(wave_sum(s) * (1.f / D) + EPS);
	v_add_f32_e32 v224, v224, v80
	v_add_f32_e32 v225, v225, v81
	v_add_f32_e32 v226, v226, v82
	v_add_f32_e32 v227, v227, v83
	v_add_f32_e32 v228, v228, v84
	v_add_f32_e32 v229, v229, v85
	v_add_f32_e32 v230, v230, v86
	v_add_f32_e32 v231, v231, v87
	v_add_f32_e32 v232, v232, v88
	v_add_f32_e32 v233, v233, v89
	v_add_f32_e32 v234, v234, v90
	v_add_f32_e32 v235, v235, v91
	v_add_f32_e32 v236, v236, v92
	v_add_f32_e32 v237, v237, v93
	v_add_f32_e32 v238, v238, v94
	v_add_f32_e32 v239, v239, v95
	s_waitcnt vmcnt(12)
	v_add_f32_e32 v224, v224, v96
	v_add_f32_e32 v225, v225, v97
	v_add_f32_e32 v226, v226, v98
	v_add_f32_e32 v227, v227, v99
	v_add_f32_e32 v228, v228, v100
	v_add_f32_e32 v229, v229, v101
	v_add_f32_e32 v230, v230, v102
	v_add_f32_e32 v231, v231, v103
	v_add_f32_e32 v232, v232, v104
	v_add_f32_e32 v233, v233, v105
	v_add_f32_e32 v234, v234, v106
	v_add_f32_e32 v235, v235, v107
	v_add_f32_e32 v236, v236, v108
	v_add_f32_e32 v237, v237, v109
	v_add_f32_e32 v238, v238, v110
	v_add_f32_e32 v239, v239, v111
	s_waitcnt vmcnt(8)
	v_add_f32_e32 v224, v224, v112
	v_add_f32_e32 v225, v225, v113
	v_add_f32_e32 v226, v226, v114
	v_add_f32_e32 v227, v227, v115
	v_add_f32_e32 v228, v228, v116
	v_add_f32_e32 v229, v229, v117
	v_add_f32_e32 v230, v230, v118
	v_add_f32_e32 v231, v231, v119
	v_add_f32_e32 v232, v232, v120
	v_add_f32_e32 v233, v233, v121
	v_add_f32_e32 v234, v234, v122
	v_add_f32_e32 v235, v235, v123
	v_add_f32_e32 v236, v236, v124
	v_add_f32_e32 v237, v237, v125
	v_add_f32_e32 v238, v238, v126
	v_add_f32_e32 v239, v239, v127
	s_waitcnt vmcnt(4)
	v_add_f32_e32 v224, v224, v128
	v_add_f32_e32 v225, v225, v129
	v_add_f32_e32 v226, v226, v130
	v_add_f32_e32 v227, v227, v131
	v_add_f32_e32 v228, v228, v132
	v_add_f32_e32 v229, v229, v133
	v_add_f32_e32 v230, v230, v134
	v_add_f32_e32 v231, v231, v135
	v_add_f32_e32 v232, v232, v136
	v_add_f32_e32 v233, v233, v137
	v_add_f32_e32 v234, v234, v138
	v_add_f32_e32 v235, v235, v139
	v_add_f32_e32 v236, v236, v140
	v_add_f32_e32 v237, v237, v141
	v_add_f32_e32 v238, v238, v142
	v_add_f32_e32 v239, v239, v143
	s_waitcnt vmcnt(0)
	v_add_f32_e32 v224, v224, v144
	v_add_f32_e32 v225, v225, v145
	v_add_f32_e32 v226, v226, v146
	v_add_f32_e32 v227, v227, v147
	v_add_f32_e32 v228, v228, v148
	v_add_f32_e32 v229, v229, v149
	v_add_f32_e32 v230, v230, v150
	v_add_f32_e32 v231, v231, v151
	v_add_f32_e32 v232, v232, v152
	v_add_f32_e32 v233, v233, v153
	v_add_f32_e32 v234, v234, v154
	v_add_f32_e32 v235, v235, v155
	v_add_f32_e32 v236, v236, v156
	v_add_f32_e32 v237, v237, v157
	v_add_f32_e32 v238, v238, v158
	v_add_f32_e32 v239, v239, v159
	global_load_dwordx4 v[32:35], v6, s[18:19]
	global_load_dwordx4 v[36:39], v6, s[18:19] offset:1024
	global_load_dwordx4 v[40:43], v6, s[18:19] offset:2048
	global_load_dwordx4 v[44:47], v6, s[18:19] offset:3072
	s_add_u32 s18, s18, 0x100000
	s_addc_u32 s19, s19, 0
	global_load_dwordx4 v[48:51], v6, s[18:19]
	global_load_dwordx4 v[52:55], v6, s[18:19] offset:1024
	global_load_dwordx4 v[56:59], v6, s[18:19] offset:2048
	global_load_dwordx4 v[60:63], v6, s[18:19] offset:3072
	s_add_u32 s18, s18, 0x100000
	s_addc_u32 s19, s19, 0
	global_load_dwordx4 v[64:67], v6, s[18:19]
	global_load_dwordx4 v[68:71], v6, s[18:19] offset:1024
	global_load_dwordx4 v[72:75], v6, s[18:19] offset:2048
	global_load_dwordx4 v[76:79], v6, s[18:19] offset:3072
	s_add_u32 s18, s18, 0x100000
	s_addc_u32 s19, s19, 0
	s_waitcnt vmcnt(8)
	v_add_f32_e32 v224, v224, v32
	v_add_f32_e32 v225, v225, v33
	v_add_f32_e32 v226, v226, v34
	v_add_f32_e32 v227, v227, v35
	v_add_f32_e32 v228, v228, v36
	v_add_f32_e32 v229, v229, v37
	v_add_f32_e32 v230, v230, v38
	v_add_f32_e32 v231, v231, v39
	v_add_f32_e32 v232, v232, v40
	v_add_f32_e32 v233, v233, v41
	v_add_f32_e32 v234, v234, v42
	v_add_f32_e32 v235, v235, v43
	v_add_f32_e32 v236, v236, v44
	v_add_f32_e32 v237, v237, v45
	v_add_f32_e32 v238, v238, v46
	v_add_f32_e32 v239, v239, v47
	s_waitcnt vmcnt(4)
	v_add_f32_e32 v224, v224, v48
	v_add_f32_e32 v225, v225, v49
	v_add_f32_e32 v226, v226, v50
	v_add_f32_e32 v227, v227, v51
	v_add_f32_e32 v228, v228, v52
	v_add_f32_e32 v229, v229, v53
	v_add_f32_e32 v230, v230, v54
	v_add_f32_e32 v231, v231, v55
	v_add_f32_e32 v232, v232, v56
	v_add_f32_e32 v233, v233, v57
	v_add_f32_e32 v234, v234, v58
	v_add_f32_e32 v235, v235, v59
	v_add_f32_e32 v236, v236, v60
	v_add_f32_e32 v237, v237, v61
	v_add_f32_e32 v238, v238, v62
	v_add_f32_e32 v239, v239, v63
	s_waitcnt vmcnt(0)
	v_add_f32_e32 v224, v224, v64
	v_add_f32_e32 v225, v225, v65
	v_add_f32_e32 v226, v226, v66
	v_add_f32_e32 v227, v227, v67
	v_add_f32_e32 v228, v228, v68
	v_add_f32_e32 v229, v229, v69
	v_add_f32_e32 v230, v230, v70
	v_add_f32_e32 v231, v231, v71
	v_add_f32_e32 v232, v232, v72
	v_add_f32_e32 v233, v233, v73
	v_add_f32_e32 v234, v234, v74
	v_add_f32_e32 v235, v235, v75
	v_add_f32_e32 v236, v236, v76
	v_add_f32_e32 v237, v237, v77
	v_add_f32_e32 v238, v238, v78
	v_add_f32_e32 v239, v239, v79
	v_cvt_pk_bf16_f32 v26, v224, v225
	v_cvt_pk_bf16_f32 v27, v226, v227
	global_store_dwordx2 v5, v[26:27], s[10:11] sc0 sc1
	v_cvt_pk_bf16_f32 v28, v228, v229
	v_cvt_pk_bf16_f32 v29, v230, v231
	global_store_dwordx2 v5, v[28:29], s[10:11] offset:512 sc0 sc1
	v_cvt_pk_bf16_f32 v30, v232, v233
	v_cvt_pk_bf16_f32 v31, v234, v235
	global_store_dwordx2 v5, v[30:31], s[10:11] offset:1024 sc0 sc1
	v_cvt_pk_bf16_f32 v32, v236, v237
	v_cvt_pk_bf16_f32 v33, v238, v239
	global_store_dwordx2 v5, v[32:33], s[10:11] offset:1536 sc0 sc1
	v_mul_f32_e32 v7, v224, v224
	v_fmac_f32_e32 v7, v225, v225
	v_fmac_f32_e32 v7, v226, v226
	v_fmac_f32_e32 v7, v227, v227
	v_fmac_f32_e32 v7, v228, v228
	v_fmac_f32_e32 v7, v229, v229
	v_fmac_f32_e32 v7, v230, v230
	v_fmac_f32_e32 v7, v231, v231
	v_fmac_f32_e32 v7, v232, v232
	v_fmac_f32_e32 v7, v233, v233
	v_fmac_f32_e32 v7, v234, v234
	v_fmac_f32_e32 v7, v235, v235
	v_fmac_f32_e32 v7, v236, v236
	v_fmac_f32_e32 v7, v237, v237
	v_fmac_f32_e32 v7, v238, v238
	v_fmac_f32_e32 v7, v239, v239
	v_xor_b32_e32 v10, 1, v2
	v_lshlrev_b32_e32 v10, 2, v10
	ds_bpermute_b32 v10, v10, v7
	s_waitcnt lgkmcnt(0)
	v_add_f32_e32 v7, v7, v10
	v_xor_b32_e32 v10, 2, v2
	v_lshlrev_b32_e32 v10, 2, v10
	ds_bpermute_b32 v10, v10, v7
	s_waitcnt lgkmcnt(0)
	v_add_f32_e32 v7, v7, v10
	v_xor_b32_e32 v10, 4, v2
	v_lshlrev_b32_e32 v10, 2, v10
	ds_bpermute_b32 v10, v10, v7
	s_waitcnt lgkmcnt(0)
	v_add_f32_e32 v7, v7, v10
	v_xor_b32_e32 v10, 8, v2
	v_lshlrev_b32_e32 v10, 2, v10
	ds_bpermute_b32 v10, v10, v7
	s_waitcnt lgkmcnt(0)
	v_add_f32_e32 v7, v7, v10
	v_xor_b32_e32 v10, 16, v2
	v_lshlrev_b32_e32 v10, 2, v10
	ds_bpermute_b32 v10, v10, v7
	s_waitcnt lgkmcnt(0)
	v_add_f32_e32 v7, v7, v10
	v_xor_b32_e32 v10, 32, v2
	v_lshlrev_b32_e32 v10, 2, v10
	ds_bpermute_b32 v10, v10, v7
	s_waitcnt lgkmcnt(0)
	v_add_f32_e32 v7, v7, v10
	v_fmamk_f32 v7, v7, 0x3a800000, v213
	v_rsq_f32_e32 v7, v7
	s_nop 0
	global_store_dword v1, v7, s[14:15] sc0 sc1
	s_branch .Lp1m_exit
; __device__ __forceinline__ void norm_phase(KP p, bool first, int nslab) {
;     ...
;         for (int j = 0; j < 4; ++j) s += (v[j][0] * v[j][0] + v[j][1] * v[j][1]) + (v[j][2] * v[j][2] + v[j][3] * v[j][3]);
;         const float rinv = rsqrtf(wave_sum(s) * (1.f / D) + EPS);
.Lnm_part2_p1:
	v_lshl_add_u32 v5, s2, 9, v0
	v_lshlrev_b32_e32 v6, 8, v5
	global_load_dwordx4 v[32:35], v6, s[12:13]
	global_load_dwordx4 v[36:39], v6, s[12:13] offset:16
	global_load_dwordx4 v[40:43], v6, s[12:13] offset:32
	global_load_dwordx4 v[44:47], v6, s[12:13] offset:48
	global_load_dwordx4 v[48:51], v6, s[12:13] offset:64
	global_load_dwordx4 v[52:55], v6, s[12:13] offset:80
	global_load_dwordx4 v[56:59], v6, s[12:13] offset:96
	global_load_dwordx4 v[60:63], v6, s[12:13] offset:112
	global_load_dwordx4 v[64:67], v6, s[12:13] offset:128
	global_load_dwordx4 v[68:71], v6, s[12:13] offset:144
	global_load_dwordx4 v[72:75], v6, s[12:13] offset:160
	global_load_dwordx4 v[76:79], v6, s[12:13] offset:176
	global_load_dwordx4 v[80:83], v6, s[12:13] offset:192
	global_load_dwordx4 v[84:87], v6, s[12:13] offset:208
	global_load_dwordx4 v[88:91], v6, s[12:13] offset:224
	global_load_dwordx4 v[92:95], v6, s[12:13] offset:240
	s_waitcnt vmcnt(0)
	v_add_f32_e32 v7, v32, v33
	v_add_f32_e32 v7, v7, v34
	v_add_f32_e32 v7, v7, v35
	v_add_f32_e32 v7, v7, v36
	v_add_f32_e32 v7, v7, v37
	v_add_f32_e32 v7, v7, v38
	v_add_f32_e32 v7, v7, v39
	v_add_f32_e32 v7, v7, v40
	v_add_f32_e32 v7, v7, v41
	v_add_f32_e32 v7, v7, v42
	v_add_f32_e32 v7, v7, v43
	v_add_f32_e32 v7, v7, v44
	v_add_f32_e32 v7, v7, v45
	v_add_f32_e32 v7, v7, v46
	v_add_f32_e32 v7, v7, v47
	v_add_f32_e32 v7, v7, v48
	v_add_f32_e32 v7, v7, v49
	v_add_f32_e32 v7, v7, v50
	v_add_f32_e32 v7, v7, v51
	v_add_f32_e32 v7, v7, v52
	v_add_f32_e32 v7, v7, v53
	v_add_f32_e32 v7, v7, v54
	v_add_f32_e32 v7, v7, v55
	v_add_f32_e32 v7, v7, v56
	v_add_f32_e32 v7, v7, v57
	v_add_f32_e32 v7, v7, v58
	v_add_f32_e32 v7, v7, v59
	v_add_f32_e32 v7, v7, v60
	v_add_f32_e32 v7, v7, v61
	v_add_f32_e32 v7, v7, v62
	v_add_f32_e32 v7, v7, v63
	v_add_f32_e32 v7, v7, v64
	v_add_f32_e32 v7, v7, v65
	v_add_f32_e32 v7, v7, v66
	v_add_f32_e32 v7, v7, v67
	v_add_f32_e32 v7, v7, v68
	v_add_f32_e32 v7, v7, v69
	v_add_f32_e32 v7, v7, v70
	v_add_f32_e32 v7, v7, v71
	v_add_f32_e32 v7, v7, v72
	v_add_f32_e32 v7, v7, v73
	v_add_f32_e32 v7, v7, v74
	v_add_f32_e32 v7, v7, v75
	v_add_f32_e32 v7, v7, v76
	v_add_f32_e32 v7, v7, v77
	v_add_f32_e32 v7, v7, v78
	v_add_f32_e32 v7, v7, v79
	v_add_f32_e32 v7, v7, v80
	v_add_f32_e32 v7, v7, v81
	v_add_f32_e32 v7, v7, v82
	v_add_f32_e32 v7, v7, v83
	v_add_f32_e32 v7, v7, v84
	v_add_f32_e32 v7, v7, v85
	v_add_f32_e32 v7, v7, v86
	v_add_f32_e32 v7, v7, v87
	v_add_f32_e32 v7, v7, v88
	v_add_f32_e32 v7, v7, v89
	v_add_f32_e32 v7, v7, v90
	v_add_f32_e32 v7, v7, v91
	v_add_f32_e32 v7, v7, v92
	v_add_f32_e32 v7, v7, v93
	v_add_f32_e32 v7, v7, v94
	v_add_f32_e32 v7, v7, v95
	v_fmamk_f32 v7, v7, 0x3a800000, v213
	v_rsq_f32_e32 v7, v7
	v_lshlrev_b32_e32 v10, 2, v5
	global_store_dword v10, v7, s[14:15] sc0 sc1

; #define LAS __attribute__((address_space(3)))
; __device__ __forceinline__ KP kargs() { KP k = (KP)__builtin_amdgcn_kernarg_segment_ptr(); asm volatile("" : "+s"(k)); return k; }
; __device__ __forceinline__ int tid_() { int t = threadIdx.x; asm volatile("" : "+v"(t)); return t; }
; __device__ __forceinline__ unsigned xb_ld(unsigned* p)              { return __hip_atomic_load(p, __ATOMIC_RELAXED, __HIP_MEMORY_SCOPE_AGENT); }
; __device__ __forceinline__ unsigned xb_add(unsigned* p, unsigned v) { return __hip_atomic_fetch_add(p, v, __ATOMIC_RELAXED, __HIP_MEMORY_SCOPE_AGENT); }
; __device__ __forceinline__ unsigned xb_xcc_id() { return (unsigned)__builtin_amdgcn_s_getreg((3 << 11) | 20) & 0xFu; }
; __device__ __forceinline__ void grid_barrier(LAS unsigned char* lds) {
;     asm volatile("s_waitcnt vmcnt(0)" ::: "memory");
;     __syncthreads();
;     if (tid_() == 0) {
;         unsigned* bar = (unsigned*)(kargs()->ws + WS_BAR);
;         volatile LAS unsigned* st = (volatile LAS unsigned*)(lds + LDS_BAR_OFF);
;         const unsigned x = xb_xcc_id();
;         __builtin_amdgcn_s_waitcnt(0);
;         unsigned nloc = st[0], nx = st[1];
;         if (nloc == 0u) { xcd_barrier_complete(bar, x, nloc, nx); st[0] = nloc; st[1] = nx; }
;         const unsigned old = xb_add(&bar[XB_XSUB(x)], 1u);
;         const unsigned gen = old / nloc;
;         if (old + 1u == (gen + 1u) * nloc) {
;             __builtin_amdgcn_fence(__ATOMIC_RELEASE, "agent");
;             asm volatile("s_waitcnt vmcnt(0)" ::: "memory");
;             const unsigned og = xb_add(&bar[XB_TOP], 1u);
;             const unsigned tg = og / nx;
;             if (og + 1u == (tg + 1u) * nx) xb_add(&bar[XB_TOPGEN], 1u);
;             else XB_SPIN(xb_ld(&bar[XB_TOPGEN]) == tg, bar);
;             __builtin_amdgcn_fence(__ATOMIC_ACQUIRE, "agent");
;             xb_add(&bar[XB_XGEN(x)], 1u);
;             asm volatile("s_waitcnt vmcnt(0)" ::: "memory");
;         } else {
;             XB_SPIN(xb_ld(&bar[XB_XGEN(x)]) == gen, bar);
;             __builtin_amdgcn_fence(__ATOMIC_ACQUIRE, "agent");
;             asm volatile("s_waitcnt vmcnt(0)" ::: "memory");
;         }
;     }
;     __syncthreads();
; }
.LBB0_88:
	s_waitcnt vmcnt(0)
	v_mov_b32_e32 v0, v209
	s_barrier
	s_nop 0
	v_cmp_eq_u32_e32 vcc, 0, v0
	s_and_saveexec_b64 s[4:5], vcc
	s_cbranch_execz .LBB0_140
	s_cmp_eq_u32 s56, 0
	s_cbranch_scc1 .Lfb1_orig
	v_readlane_b32 s12, v255, 8
	v_readlane_b32 s13, v255, 9
	v_mov_b32_e32 v19, 1
	v_mov_b32_e32 v22, 0
	s_lshl_b32 s35, s56, 3
	s_add_i32 s35, s35, 15872
	s_add_u32 s12, s12, s35
	s_addc_u32 s13, s13, 0
	global_atomic_add v22, v19, s[12:13]
	s_waitcnt vmcnt(0)
	s_branch .LBB0_140

.LBB0_164:
	s_cmp_lg_u32 s48, 0
	s_cbranch_scc1 .Lfw_p2_done
	s_cmp_eq_u32 s56, 0
	s_cbranch_scc1 .Lfw_p2_done
	s_lshl_b32 s14, s56, 3
	s_add_u32 s12, s64, 0x13ce3e00
	s_addc_u32 s13, s65, 0
	s_add_u32 s12, s12, s14
	s_addc_u32 s13, s13, 0
	v_mov_b32_e32 v191, 0
	s_mov_b32 s14, 0
.Lfw_p2_loop:
	global_load_dword v176, v191, s[12:13] sc0 sc1
	s_waitcnt vmcnt(0)
	v_readfirstlane_b32 s15, v176
	s_nop 3
	s_cmpk_ge_u32 s15, 0x100
	s_cbranch_scc1 .Lfw_p2_done
	s_sleep 1
	s_add_i32 s14, s14, 1
	s_cmp_lt_u32 s14, 0x100000
	s_cbranch_scc1 .Lfw_p2_loop

; #define LAS __attribute__((address_space(3)))
; __device__ __forceinline__ KP kargs() { KP k = (KP)__builtin_amdgcn_kernarg_segment_ptr(); asm volatile("" : "+s"(k)); return k; }
; __device__ __forceinline__ int tid_() { int t = threadIdx.x; asm volatile("" : "+v"(t)); return t; }
; __device__ __forceinline__ unsigned xb_ld(unsigned* p)              { return __hip_atomic_load(p, __ATOMIC_RELAXED, __HIP_MEMORY_SCOPE_AGENT); }
; __device__ __forceinline__ unsigned xb_add(unsigned* p, unsigned v) { return __hip_atomic_fetch_add(p, v, __ATOMIC_RELAXED, __HIP_MEMORY_SCOPE_AGENT); }
; __device__ __forceinline__ unsigned xb_xcc_id() { return (unsigned)__builtin_amdgcn_s_getreg((3 << 11) | 20) & 0xFu; }
; #define XB_SPIN(cond, bar) do { unsigned _sp = 0; while (cond) { __builtin_amdgcn_s_sleep(1); \
;     if ((++_sp & 255u) == 0u) { if (xb_ld(&(bar)[XB_TMO])) break; if (_sp > XB_SPIN_CAP) { atomicAdd(&(bar)[XB_TMO], 1u); break; } } } } while (0)
; __device__ __forceinline__ void grid_barrier(LAS unsigned char* lds) {
;     ...
;     if (tid_() == 0) {
;         unsigned* bar = (unsigned*)(kargs()->ws + WS_BAR);
;         volatile LAS unsigned* st = (volatile LAS unsigned*)(lds + LDS_BAR_OFF);
;         const unsigned x = xb_xcc_id();
;         __builtin_amdgcn_s_waitcnt(0);
;         unsigned nloc = st[0], nx = st[1];
;         if (nloc == 0u) { xcd_barrier_complete(bar, x, nloc, nx); st[0] = nloc; st[1] = nx; }
;         const unsigned old = xb_add(&bar[XB_XSUB(x)], 1u);
;         const unsigned gen = old / nloc;
;         if (old + 1u == (gen + 1u) * nloc) {
;             __builtin_amdgcn_fence(__ATOMIC_RELEASE, "agent");
;             asm volatile("s_waitcnt vmcnt(0)" ::: "memory");
;             const unsigned og = xb_add(&bar[XB_TOP], 1u);
;             const unsigned tg = og / nx;
;             if (og + 1u == (tg + 1u) * nx) xb_add(&bar[XB_TOPGEN], 1u);
;             else XB_SPIN(xb_ld(&bar[XB_TOPGEN]) == tg, bar);
;             __builtin_amdgcn_fence(__ATOMIC_ACQUIRE, "agent");
;             xb_add(&bar[XB_XGEN(x)], 1u);
;             asm volatile("s_waitcnt vmcnt(0)" ::: "memory");
;         } else {
;             XB_SPIN(xb_ld(&bar[XB_XGEN(x)]) == gen, bar);
;             __builtin_amdgcn_fence(__ATOMIC_ACQUIRE, "agent");
;             asm volatile("s_waitcnt vmcnt(0)" ::: "memory");
;         }
.LBB0_264:
	s_waitcnt vmcnt(0)
	v_mov_b32_e32 v0, v209
	s_waitcnt vmcnt(0)
	s_barrier
	s_nop 0
	v_cmp_eq_u32_e32 vcc, 0, v0
	s_and_saveexec_b64 s[4:5], vcc
	s_movk_i32 s0, 0x400
	s_mov_b32 s1, 0xfe03f81
	s_mov_b32 s20, 0x800000
	v_readlane_b32 s52, v255, 3
	v_readlane_b32 s50, v255, 4
	s_movk_i32 s23, 0x3000
	s_movk_i32 s43, 0x2000
	s_movk_i32 s21, 0x810
	s_cbranch_execz .LBB0_316
	v_readlane_b32 s12, v255, 8
	v_readlane_b32 s13, v255, 9
	v_mov_b32_e32 v18, 0x20000
	ds_read2_b32 v[20:21], v18 offset1:1
	s_getreg_b32 s14, hwreg(HW_REG_XCC_ID, 0, 4)
	s_and_b32 s14, s14, 15
	s_mul_i32 s32, s56, 9
	s_add_i32 s32, s32, 1
	s_add_i32 s34, s32, 1
	v_mov_b32_e32 v19, 1
	v_mov_b32_e32 v22, 0
	s_waitcnt lgkmcnt(0)
	v_readfirstlane_b32 s24, v20
	v_readfirstlane_b32 s25, v21
	s_lshl_b32 s35, s14, 8
	s_add_u32 s70, s12, s35
	s_addc_u32 s71, s13, 0
	s_add_u32 s72, s70, 0x2400
	s_addc_u32 s73, s71, 0
	s_add_u32 s70, s70, 0x1400
	s_addc_u32 s71, s71, 0
	global_atomic_add v23, v22, v19, s[70:71] sc0
	s_mul_i32 s57, s34, s24
	s_waitcnt vmcnt(0)
	v_readfirstlane_b32 s44, v23
	s_nop 3
	s_add_i32 s44, s44, 1
	s_cmp_lg_u32 s44, s57
	s_cbranch_scc1 .Lfb2_spin
	buffer_wbl2 sc1
	s_waitcnt vmcnt(0)
	s_add_u32 s98, s12, 0x3400
	s_addc_u32 s99, s13, 0
	global_atomic_add v23, v22, v19, s[98:99] sc0
	s_mul_i32 s57, s34, s25
	s_waitcnt vmcnt(0)
	v_readfirstlane_b32 s44, v23
	s_nop 3
	s_add_i32 s44, s44, 1
	s_cmp_lg_u32 s44, s57
	s_cbranch_scc1 .Lfb2_spin
	global_atomic_add v22, v19, s[98:99] offset:256
	s_add_u32 s98, s12, 0x2400
	s_addc_u32 s99, s13, 0
	global_atomic_add v22, v19, s[98:99]
	global_atomic_add v22, v19, s[98:99] offset:256
	global_atomic_add v22, v19, s[98:99] offset:512
	global_atomic_add v22, v19, s[98:99] offset:768
	global_atomic_add v22, v19, s[98:99] offset:1024
	global_atomic_add v22, v19, s[98:99] offset:1280
	global_atomic_add v22, v19, s[98:99] offset:1536
	global_atomic_add v22, v19, s[98:99] offset:1792
	global_atomic_add v22, v19, s[98:99] offset:2048
	global_atomic_add v22, v19, s[98:99] offset:2304
	global_atomic_add v22, v19, s[98:99] offset:2560
	global_atomic_add v22, v19, s[98:99] offset:2816
	global_atomic_add v22, v19, s[98:99] offset:3072
	global_atomic_add v22, v19, s[98:99] offset:3328
	global_atomic_add v22, v19, s[98:99] offset:3584
	global_atomic_add v22, v19, s[98:99] offset:3840

; #define LAS __attribute__((address_space(3)))
; __device__ __forceinline__ KP kargs() { KP k = (KP)__builtin_amdgcn_kernarg_segment_ptr(); asm volatile("" : "+s"(k)); return k; }
; __device__ __forceinline__ int tid_() { int t = threadIdx.x; asm volatile("" : "+v"(t)); return t; }
; __device__ __forceinline__ unsigned xb_ld(unsigned* p)              { return __hip_atomic_load(p, __ATOMIC_RELAXED, __HIP_MEMORY_SCOPE_AGENT); }
; __device__ __forceinline__ unsigned xb_add(unsigned* p, unsigned v) { return __hip_atomic_fetch_add(p, v, __ATOMIC_RELAXED, __HIP_MEMORY_SCOPE_AGENT); }
; __device__ __forceinline__ unsigned xb_xcc_id() { return (unsigned)__builtin_amdgcn_s_getreg((3 << 11) | 20) & 0xFu; }
; #define XB_SPIN(cond, bar) do { unsigned _sp = 0; while (cond) { __builtin_amdgcn_s_sleep(1); \
;     if ((++_sp & 255u) == 0u) { if (xb_ld(&(bar)[XB_TMO])) break; if (_sp > XB_SPIN_CAP) { atomicAdd(&(bar)[XB_TMO], 1u); break; } } } } while (0)
; __device__ __forceinline__ void grid_barrier(LAS unsigned char* lds) {
;     ...
;     if (tid_() == 0) {
;         unsigned* bar = (unsigned*)(kargs()->ws + WS_BAR);
;         volatile LAS unsigned* st = (volatile LAS unsigned*)(lds + LDS_BAR_OFF);
;         const unsigned x = xb_xcc_id();
;         __builtin_amdgcn_s_waitcnt(0);
;         unsigned nloc = st[0], nx = st[1];
;         if (nloc == 0u) { xcd_barrier_complete(bar, x, nloc, nx); st[0] = nloc; st[1] = nx; }
;         const unsigned old = xb_add(&bar[XB_XSUB(x)], 1u);
;         const unsigned gen = old / nloc;
;         if (old + 1u == (gen + 1u) * nloc) {
;             __builtin_amdgcn_fence(__ATOMIC_RELEASE, "agent");
;             asm volatile("s_waitcnt vmcnt(0)" ::: "memory");
;             const unsigned og = xb_add(&bar[XB_TOP], 1u);
;             const unsigned tg = og / nx;
;             if (og + 1u == (tg + 1u) * nx) xb_add(&bar[XB_TOPGEN], 1u);
;             else XB_SPIN(xb_ld(&bar[XB_TOPGEN]) == tg, bar);
;             __builtin_amdgcn_fence(__ATOMIC_ACQUIRE, "agent");
;             xb_add(&bar[XB_XGEN(x)], 1u);
;             asm volatile("s_waitcnt vmcnt(0)" ::: "memory");
;         } else {
;             XB_SPIN(xb_ld(&bar[XB_XGEN(x)]) == gen, bar);
;             __builtin_amdgcn_fence(__ATOMIC_ACQUIRE, "agent");
;             asm volatile("s_waitcnt vmcnt(0)" ::: "memory");
;         }
.LBB0_357:
	s_waitcnt vmcnt(0)
	v_mov_b32_e32 v0, v209
	s_waitcnt lgkmcnt(0)
	s_barrier
	s_nop 0
	v_cmp_eq_u32_e32 vcc, 0, v0
	s_and_saveexec_b64 s[4:5], vcc
	s_cbranch_execz .LBB0_409
	v_readlane_b32 s12, v255, 8
	v_readlane_b32 s13, v255, 9
	v_mov_b32_e32 v18, 0x20000
	ds_read2_b32 v[20:21], v18 offset1:1
	s_getreg_b32 s14, hwreg(HW_REG_XCC_ID, 0, 4)
	s_and_b32 s14, s14, 15
	s_mul_i32 s32, s56, 9
	s_add_i32 s32, s32, 2
	s_add_i32 s34, s32, 1
	v_mov_b32_e32 v19, 1
	v_mov_b32_e32 v22, 0
	s_waitcnt lgkmcnt(0)
	v_readfirstlane_b32 s24, v20
	v_readfirstlane_b32 s25, v21
	s_lshl_b32 s35, s14, 8
	s_add_u32 s70, s12, s35
	s_addc_u32 s71, s13, 0
	s_add_u32 s72, s70, 0x2400
	s_addc_u32 s73, s71, 0
	s_add_u32 s70, s70, 0x1400
	s_addc_u32 s71, s71, 0
	global_atomic_add v23, v22, v19, s[70:71] sc0
	s_mul_i32 s57, s34, s24
	s_waitcnt vmcnt(0)
	v_readfirstlane_b32 s44, v23
	s_nop 3
	s_add_i32 s44, s44, 1
	s_cmp_lg_u32 s44, s57
	s_cbranch_scc1 .Lfb3_spin
	buffer_wbl2 sc1
	s_waitcnt vmcnt(0)
	s_add_u32 s98, s12, 0x3400
	s_addc_u32 s99, s13, 0
	global_atomic_add v23, v22, v19, s[98:99] sc0
	s_mul_i32 s57, s34, s25
	s_waitcnt vmcnt(0)
	v_readfirstlane_b32 s44, v23
	s_nop 3
	s_add_i32 s44, s44, 1
	s_cmp_lg_u32 s44, s57
	s_cbranch_scc1 .Lfb3_spin
	global_atomic_add v22, v19, s[98:99] offset:256
	s_add_u32 s98, s12, 0x2400
	s_addc_u32 s99, s13, 0
	global_atomic_add v22, v19, s[98:99]
	global_atomic_add v22, v19, s[98:99] offset:256
	global_atomic_add v22, v19, s[98:99] offset:512
	global_atomic_add v22, v19, s[98:99] offset:768
	global_atomic_add v22, v19, s[98:99] offset:1024
	global_atomic_add v22, v19, s[98:99] offset:1280
	global_atomic_add v22, v19, s[98:99] offset:1536
	global_atomic_add v22, v19, s[98:99] offset:1792
	global_atomic_add v22, v19, s[98:99] offset:2048
	global_atomic_add v22, v19, s[98:99] offset:2304
	global_atomic_add v22, v19, s[98:99] offset:2560
	global_atomic_add v22, v19, s[98:99] offset:2816
	global_atomic_add v22, v19, s[98:99] offset:3072
	global_atomic_add v22, v19, s[98:99] offset:3328
	global_atomic_add v22, v19, s[98:99] offset:3584
	global_atomic_add v22, v19, s[98:99] offset:3840

; #define LAS __attribute__((address_space(3)))
; __device__ __forceinline__ KP kargs() { KP k = (KP)__builtin_amdgcn_kernarg_segment_ptr(); asm volatile("" : "+s"(k)); return k; }
; __device__ __forceinline__ int tid_() { int t = threadIdx.x; asm volatile("" : "+v"(t)); return t; }
; __device__ __forceinline__ unsigned xb_ld(unsigned* p)              { return __hip_atomic_load(p, __ATOMIC_RELAXED, __HIP_MEMORY_SCOPE_AGENT); }
; __device__ __forceinline__ unsigned xb_add(unsigned* p, unsigned v) { return __hip_atomic_fetch_add(p, v, __ATOMIC_RELAXED, __HIP_MEMORY_SCOPE_AGENT); }
; __device__ __forceinline__ unsigned xb_xcc_id() { return (unsigned)__builtin_amdgcn_s_getreg((3 << 11) | 20) & 0xFu; }
; #define XB_SPIN(cond, bar) do { unsigned _sp = 0; while (cond) { __builtin_amdgcn_s_sleep(1); \
;     if ((++_sp & 255u) == 0u) { if (xb_ld(&(bar)[XB_TMO])) break; if (_sp > XB_SPIN_CAP) { atomicAdd(&(bar)[XB_TMO], 1u); break; } } } } while (0)
; __device__ __forceinline__ void grid_barrier(LAS unsigned char* lds) {
;     ...
;     if (tid_() == 0) {
;         unsigned* bar = (unsigned*)(kargs()->ws + WS_BAR);
;         volatile LAS unsigned* st = (volatile LAS unsigned*)(lds + LDS_BAR_OFF);
;         const unsigned x = xb_xcc_id();
;         __builtin_amdgcn_s_waitcnt(0);
;         unsigned nloc = st[0], nx = st[1];
;         if (nloc == 0u) { xcd_barrier_complete(bar, x, nloc, nx); st[0] = nloc; st[1] = nx; }
;         const unsigned old = xb_add(&bar[XB_XSUB(x)], 1u);
;         const unsigned gen = old / nloc;
;         if (old + 1u == (gen + 1u) * nloc) {
;             __builtin_amdgcn_fence(__ATOMIC_RELEASE, "agent");
;             asm volatile("s_waitcnt vmcnt(0)" ::: "memory");
;             const unsigned og = xb_add(&bar[XB_TOP], 1u);
;             const unsigned tg = og / nx;
;             if (og + 1u == (tg + 1u) * nx) xb_add(&bar[XB_TOPGEN], 1u);
;             else XB_SPIN(xb_ld(&bar[XB_TOPGEN]) == tg, bar);
;             __builtin_amdgcn_fence(__ATOMIC_ACQUIRE, "agent");
;             xb_add(&bar[XB_XGEN(x)], 1u);
;             asm volatile("s_waitcnt vmcnt(0)" ::: "memory");
;         } else {
;             XB_SPIN(xb_ld(&bar[XB_XGEN(x)]) == gen, bar);
;             __builtin_amdgcn_fence(__ATOMIC_ACQUIRE, "agent");
;             asm volatile("s_waitcnt vmcnt(0)" ::: "memory");
;         }
.LBB0_426:
	s_or_b64 exec, exec, s[8:9]
	s_waitcnt vmcnt(0)
	v_mov_b32_e32 v0, v209
	s_barrier
	s_nop 0
	v_cmp_eq_u32_e32 vcc, 0, v0
	s_and_saveexec_b64 s[4:5], vcc
	s_cbranch_execz .LBB0_478
	v_readlane_b32 s12, v255, 8
	v_readlane_b32 s13, v255, 9
	v_mov_b32_e32 v18, 0x20000
	ds_read2_b32 v[20:21], v18 offset1:1
	s_getreg_b32 s14, hwreg(HW_REG_XCC_ID, 0, 4)
	s_and_b32 s14, s14, 15
	s_mul_i32 s32, s56, 9
	s_add_i32 s32, s32, 3
	s_add_i32 s34, s32, 1
	v_mov_b32_e32 v19, 1
	v_mov_b32_e32 v22, 0
	s_waitcnt lgkmcnt(0)
	v_readfirstlane_b32 s24, v20
	v_readfirstlane_b32 s25, v21
	s_lshl_b32 s35, s14, 8
	s_add_u32 s70, s12, s35
	s_addc_u32 s71, s13, 0
	s_add_u32 s72, s70, 0x2400
	s_addc_u32 s73, s71, 0
	s_add_u32 s70, s70, 0x1400
	s_addc_u32 s71, s71, 0
	global_atomic_add v23, v22, v19, s[70:71] sc0
	s_mul_i32 s57, s34, s24
	s_waitcnt vmcnt(0)
	v_readfirstlane_b32 s44, v23
	s_nop 3
	s_add_i32 s44, s44, 1
	s_cmp_lg_u32 s44, s57
	s_cbranch_scc1 .Lfb4_spin
	buffer_wbl2 sc1
	s_waitcnt vmcnt(0)
	s_add_u32 s98, s12, 0x3400
	s_addc_u32 s99, s13, 0
	global_atomic_add v23, v22, v19, s[98:99] sc0
	s_mul_i32 s57, s34, s25
	s_waitcnt vmcnt(0)
	v_readfirstlane_b32 s44, v23
	s_nop 3
	s_add_i32 s44, s44, 1
	s_cmp_lg_u32 s44, s57
	s_cbranch_scc1 .Lfb4_spin
	global_atomic_add v22, v19, s[98:99] offset:256
	s_add_u32 s98, s12, 0x2400
	s_addc_u32 s99, s13, 0
	global_atomic_add v22, v19, s[98:99]
	global_atomic_add v22, v19, s[98:99] offset:256
	global_atomic_add v22, v19, s[98:99] offset:512
	global_atomic_add v22, v19, s[98:99] offset:768
	global_atomic_add v22, v19, s[98:99] offset:1024
	global_atomic_add v22, v19, s[98:99] offset:1280
	global_atomic_add v22, v19, s[98:99] offset:1536
	global_atomic_add v22, v19, s[98:99] offset:1792
	global_atomic_add v22, v19, s[98:99] offset:2048
	global_atomic_add v22, v19, s[98:99] offset:2304
	global_atomic_add v22, v19, s[98:99] offset:2560
	global_atomic_add v22, v19, s[98:99] offset:2816
	global_atomic_add v22, v19, s[98:99] offset:3072
	global_atomic_add v22, v19, s[98:99] offset:3328
	global_atomic_add v22, v19, s[98:99] offset:3584
	global_atomic_add v22, v19, s[98:99] offset:3840

; #define LAS __attribute__((address_space(3)))
; __device__ __forceinline__ KP kargs() { KP k = (KP)__builtin_amdgcn_kernarg_segment_ptr(); asm volatile("" : "+s"(k)); return k; }
; __device__ __forceinline__ int tid_() { int t = threadIdx.x; asm volatile("" : "+v"(t)); return t; }
; __device__ __forceinline__ unsigned xb_ld(unsigned* p)              { return __hip_atomic_load(p, __ATOMIC_RELAXED, __HIP_MEMORY_SCOPE_AGENT); }
; __device__ __forceinline__ unsigned xb_add(unsigned* p, unsigned v) { return __hip_atomic_fetch_add(p, v, __ATOMIC_RELAXED, __HIP_MEMORY_SCOPE_AGENT); }
; __device__ __forceinline__ unsigned xb_xcc_id() { return (unsigned)__builtin_amdgcn_s_getreg((3 << 11) | 20) & 0xFu; }
; #define XB_SPIN(cond, bar) do { unsigned _sp = 0; while (cond) { __builtin_amdgcn_s_sleep(1); \
;     if ((++_sp & 255u) == 0u) { if (xb_ld(&(bar)[XB_TMO])) break; if (_sp > XB_SPIN_CAP) { atomicAdd(&(bar)[XB_TMO], 1u); break; } } } } while (0)
; __device__ __forceinline__ void grid_barrier(LAS unsigned char* lds) {
;     ...
;     if (tid_() == 0) {
;         unsigned* bar = (unsigned*)(kargs()->ws + WS_BAR);
;         volatile LAS unsigned* st = (volatile LAS unsigned*)(lds + LDS_BAR_OFF);
;         const unsigned x = xb_xcc_id();
;         __builtin_amdgcn_s_waitcnt(0);
;         unsigned nloc = st[0], nx = st[1];
;         if (nloc == 0u) { xcd_barrier_complete(bar, x, nloc, nx); st[0] = nloc; st[1] = nx; }
;         const unsigned old = xb_add(&bar[XB_XSUB(x)], 1u);
;         const unsigned gen = old / nloc;
;         if (old + 1u == (gen + 1u) * nloc) {
;             __builtin_amdgcn_fence(__ATOMIC_RELEASE, "agent");
;             asm volatile("s_waitcnt vmcnt(0)" ::: "memory");
;             const unsigned og = xb_add(&bar[XB_TOP], 1u);
;             const unsigned tg = og / nx;
;             if (og + 1u == (tg + 1u) * nx) xb_add(&bar[XB_TOPGEN], 1u);
;             else XB_SPIN(xb_ld(&bar[XB_TOPGEN]) == tg, bar);
;             __builtin_amdgcn_fence(__ATOMIC_ACQUIRE, "agent");
;             xb_add(&bar[XB_XGEN(x)], 1u);
;             asm volatile("s_waitcnt vmcnt(0)" ::: "memory");
;         } else {
;             XB_SPIN(xb_ld(&bar[XB_XGEN(x)]) == gen, bar);
;             __builtin_amdgcn_fence(__ATOMIC_ACQUIRE, "agent");
;             asm volatile("s_waitcnt vmcnt(0)" ::: "memory");
;         }
.LBB0_587:
	s_waitcnt vmcnt(0)
	v_mov_b32_e32 v0, v209
	s_waitcnt vmcnt(0) lgkmcnt(0)
	s_barrier
	s_nop 0
	v_cmp_eq_u32_e32 vcc, 0, v0
	s_and_saveexec_b64 s[4:5], vcc
	s_mov_b64 s[74:75], 0x48000
	s_cbranch_execz .LBB0_639
	v_readlane_b32 s12, v255, 8
	v_readlane_b32 s13, v255, 9
	v_mov_b32_e32 v18, 0x20000
	ds_read2_b32 v[20:21], v18 offset1:1
	s_getreg_b32 s14, hwreg(HW_REG_XCC_ID, 0, 4)
	s_and_b32 s14, s14, 15
	s_mul_i32 s32, s56, 9
	s_add_i32 s32, s32, 4
	s_add_i32 s34, s32, 1
	v_mov_b32_e32 v19, 1
	v_mov_b32_e32 v22, 0
	s_waitcnt lgkmcnt(0)
	v_readfirstlane_b32 s24, v20
	v_readfirstlane_b32 s25, v21
	s_lshl_b32 s35, s14, 8
	s_add_u32 s70, s12, s35
	s_addc_u32 s71, s13, 0
	s_add_u32 s72, s70, 0x2400
	s_addc_u32 s73, s71, 0
	s_add_u32 s70, s70, 0x1400
	s_addc_u32 s71, s71, 0
	global_atomic_add v23, v22, v19, s[70:71] sc0
	s_mul_i32 s57, s34, s24
	s_waitcnt vmcnt(0)
	v_readfirstlane_b32 s44, v23
	s_nop 3
	s_add_i32 s44, s44, 1
	s_cmp_lg_u32 s44, s57
	s_cbranch_scc1 .Lfb5_spin
	buffer_wbl2 sc1
	s_waitcnt vmcnt(0)
	s_add_u32 s98, s12, 0x3400
	s_addc_u32 s99, s13, 0
	global_atomic_add v23, v22, v19, s[98:99] sc0
	s_mul_i32 s57, s34, s25
	s_waitcnt vmcnt(0)
	v_readfirstlane_b32 s44, v23
	s_nop 3
	s_add_i32 s44, s44, 1
	s_cmp_lg_u32 s44, s57
	s_cbranch_scc1 .Lfb5_spin
	global_atomic_add v22, v19, s[98:99] offset:256
	s_add_u32 s98, s12, 0x2400
	s_addc_u32 s99, s13, 0
	global_atomic_add v22, v19, s[98:99]
	global_atomic_add v22, v19, s[98:99] offset:256
	global_atomic_add v22, v19, s[98:99] offset:512
	global_atomic_add v22, v19, s[98:99] offset:768
	global_atomic_add v22, v19, s[98:99] offset:1024
	global_atomic_add v22, v19, s[98:99] offset:1280
	global_atomic_add v22, v19, s[98:99] offset:1536
	global_atomic_add v22, v19, s[98:99] offset:1792
	global_atomic_add v22, v19, s[98:99] offset:2048
	global_atomic_add v22, v19, s[98:99] offset:2304
	global_atomic_add v22, v19, s[98:99] offset:2560
	global_atomic_add v22, v19, s[98:99] offset:2816
	global_atomic_add v22, v19, s[98:99] offset:3072
	global_atomic_add v22, v19, s[98:99] offset:3328
	global_atomic_add v22, v19, s[98:99] offset:3584
	global_atomic_add v22, v19, s[98:99] offset:3840

; #define LAS __attribute__((address_space(3)))
; __device__ __forceinline__ KP kargs() { KP k = (KP)__builtin_amdgcn_kernarg_segment_ptr(); asm volatile("" : "+s"(k)); return k; }
; __device__ __forceinline__ int tid_() { int t = threadIdx.x; asm volatile("" : "+v"(t)); return t; }
; __device__ __forceinline__ unsigned xb_ld(unsigned* p)              { return __hip_atomic_load(p, __ATOMIC_RELAXED, __HIP_MEMORY_SCOPE_AGENT); }
; __device__ __forceinline__ unsigned xb_add(unsigned* p, unsigned v) { return __hip_atomic_fetch_add(p, v, __ATOMIC_RELAXED, __HIP_MEMORY_SCOPE_AGENT); }
; __device__ __forceinline__ unsigned xb_xcc_id() { return (unsigned)__builtin_amdgcn_s_getreg((3 << 11) | 20) & 0xFu; }
; #define XB_SPIN(cond, bar) do { unsigned _sp = 0; while (cond) { __builtin_amdgcn_s_sleep(1); \
;     if ((++_sp & 255u) == 0u) { if (xb_ld(&(bar)[XB_TMO])) break; if (_sp > XB_SPIN_CAP) { atomicAdd(&(bar)[XB_TMO], 1u); break; } } } } while (0)
; __device__ __forceinline__ void grid_barrier(LAS unsigned char* lds) {
;     ...
;     if (tid_() == 0) {
;         unsigned* bar = (unsigned*)(kargs()->ws + WS_BAR);
;         volatile LAS unsigned* st = (volatile LAS unsigned*)(lds + LDS_BAR_OFF);
;         const unsigned x = xb_xcc_id();
;         __builtin_amdgcn_s_waitcnt(0);
;         unsigned nloc = st[0], nx = st[1];
;         if (nloc == 0u) { xcd_barrier_complete(bar, x, nloc, nx); st[0] = nloc; st[1] = nx; }
;         const unsigned old = xb_add(&bar[XB_XSUB(x)], 1u);
;         const unsigned gen = old / nloc;
;         if (old + 1u == (gen + 1u) * nloc) {
;             __builtin_amdgcn_fence(__ATOMIC_RELEASE, "agent");
;             asm volatile("s_waitcnt vmcnt(0)" ::: "memory");
;             const unsigned og = xb_add(&bar[XB_TOP], 1u);
;             const unsigned tg = og / nx;
;             if (og + 1u == (tg + 1u) * nx) xb_add(&bar[XB_TOPGEN], 1u);
;             else XB_SPIN(xb_ld(&bar[XB_TOPGEN]) == tg, bar);
;             __builtin_amdgcn_fence(__ATOMIC_ACQUIRE, "agent");
;             xb_add(&bar[XB_XGEN(x)], 1u);
;             asm volatile("s_waitcnt vmcnt(0)" ::: "memory");
;         } else {
;             XB_SPIN(xb_ld(&bar[XB_XGEN(x)]) == gen, bar);
;             __builtin_amdgcn_fence(__ATOMIC_ACQUIRE, "agent");
;             asm volatile("s_waitcnt vmcnt(0)" ::: "memory");
;         }
.LBB0_642:
	s_waitcnt vmcnt(0)
	v_mov_b32_e32 v0, v209
	s_barrier
	s_nop 0
	v_cmp_eq_u32_e32 vcc, 0, v0
	s_and_saveexec_b64 s[4:5], vcc
	s_cbranch_execz .LBB0_694
	v_readlane_b32 s12, v255, 8
	v_readlane_b32 s13, v255, 9
	v_mov_b32_e32 v18, 0x20000
	ds_read2_b32 v[20:21], v18 offset1:1
	s_getreg_b32 s14, hwreg(HW_REG_XCC_ID, 0, 4)
	s_and_b32 s14, s14, 15
	s_mul_i32 s32, s56, 9
	s_add_i32 s32, s32, 5
	s_add_i32 s34, s32, 1
	v_mov_b32_e32 v19, 1
	v_mov_b32_e32 v22, 0
	s_waitcnt lgkmcnt(0)
	v_readfirstlane_b32 s24, v20
	v_readfirstlane_b32 s25, v21
	s_lshl_b32 s35, s14, 8
	s_add_u32 s70, s12, s35
	s_addc_u32 s71, s13, 0
	s_add_u32 s72, s70, 0x2400
	s_addc_u32 s73, s71, 0
	s_add_u32 s70, s70, 0x1400
	s_addc_u32 s71, s71, 0
	global_atomic_add v23, v22, v19, s[70:71] sc0
	s_mul_i32 s57, s34, s24
	s_waitcnt vmcnt(0)
	v_readfirstlane_b32 s44, v23
	s_nop 3
	s_add_i32 s44, s44, 1
	s_cmp_lg_u32 s44, s57
	s_cbranch_scc1 .Lfb6_spin
	buffer_wbl2 sc1
	s_waitcnt vmcnt(0)
	s_add_u32 s98, s12, 0x3400
	s_addc_u32 s99, s13, 0
	global_atomic_add v23, v22, v19, s[98:99] sc0
	s_mul_i32 s57, s34, s25
	s_waitcnt vmcnt(0)
	v_readfirstlane_b32 s44, v23
	s_nop 3
	s_add_i32 s44, s44, 1
	s_cmp_lg_u32 s44, s57
	s_cbranch_scc1 .Lfb6_spin
	global_atomic_add v22, v19, s[98:99] offset:256
	s_add_u32 s98, s12, 0x2400
	s_addc_u32 s99, s13, 0
	global_atomic_add v22, v19, s[98:99]
	global_atomic_add v22, v19, s[98:99] offset:256
	global_atomic_add v22, v19, s[98:99] offset:512
	global_atomic_add v22, v19, s[98:99] offset:768
	global_atomic_add v22, v19, s[98:99] offset:1024
	global_atomic_add v22, v19, s[98:99] offset:1280
	global_atomic_add v22, v19, s[98:99] offset:1536
	global_atomic_add v22, v19, s[98:99] offset:1792
	global_atomic_add v22, v19, s[98:99] offset:2048
	global_atomic_add v22, v19, s[98:99] offset:2304
	global_atomic_add v22, v19, s[98:99] offset:2560
	global_atomic_add v22, v19, s[98:99] offset:2816
	global_atomic_add v22, v19, s[98:99] offset:3072
	global_atomic_add v22, v19, s[98:99] offset:3328
	global_atomic_add v22, v19, s[98:99] offset:3584
	global_atomic_add v22, v19, s[98:99] offset:3840

; #define LAS __attribute__((address_space(3)))
; __device__ __forceinline__ KP kargs() { KP k = (KP)__builtin_amdgcn_kernarg_segment_ptr(); asm volatile("" : "+s"(k)); return k; }
; __device__ __forceinline__ int tid_() { int t = threadIdx.x; asm volatile("" : "+v"(t)); return t; }
; __device__ __forceinline__ unsigned xb_ld(unsigned* p)              { return __hip_atomic_load(p, __ATOMIC_RELAXED, __HIP_MEMORY_SCOPE_AGENT); }
; __device__ __forceinline__ unsigned xb_add(unsigned* p, unsigned v) { return __hip_atomic_fetch_add(p, v, __ATOMIC_RELAXED, __HIP_MEMORY_SCOPE_AGENT); }
; __device__ __forceinline__ unsigned xb_xcc_id() { return (unsigned)__builtin_amdgcn_s_getreg((3 << 11) | 20) & 0xFu; }
; #define XB_SPIN(cond, bar) do { unsigned _sp = 0; while (cond) { __builtin_amdgcn_s_sleep(1); \
;     if ((++_sp & 255u) == 0u) { if (xb_ld(&(bar)[XB_TMO])) break; if (_sp > XB_SPIN_CAP) { atomicAdd(&(bar)[XB_TMO], 1u); break; } } } } while (0)
; __device__ __forceinline__ void grid_barrier(LAS unsigned char* lds) {
;     ...
;     if (tid_() == 0) {
;         unsigned* bar = (unsigned*)(kargs()->ws + WS_BAR);
;         volatile LAS unsigned* st = (volatile LAS unsigned*)(lds + LDS_BAR_OFF);
;         const unsigned x = xb_xcc_id();
;         __builtin_amdgcn_s_waitcnt(0);
;         unsigned nloc = st[0], nx = st[1];
;         if (nloc == 0u) { xcd_barrier_complete(bar, x, nloc, nx); st[0] = nloc; st[1] = nx; }
;         const unsigned old = xb_add(&bar[XB_XSUB(x)], 1u);
;         const unsigned gen = old / nloc;
;         if (old + 1u == (gen + 1u) * nloc) {
;             __builtin_amdgcn_fence(__ATOMIC_RELEASE, "agent");
;             asm volatile("s_waitcnt vmcnt(0)" ::: "memory");
;             const unsigned og = xb_add(&bar[XB_TOP], 1u);
;             const unsigned tg = og / nx;
;             if (og + 1u == (tg + 1u) * nx) xb_add(&bar[XB_TOPGEN], 1u);
;             else XB_SPIN(xb_ld(&bar[XB_TOPGEN]) == tg, bar);
;             __builtin_amdgcn_fence(__ATOMIC_ACQUIRE, "agent");
;             xb_add(&bar[XB_XGEN(x)], 1u);
;             asm volatile("s_waitcnt vmcnt(0)" ::: "memory");
;         } else {
;             XB_SPIN(xb_ld(&bar[XB_XGEN(x)]) == gen, bar);
;             __builtin_amdgcn_fence(__ATOMIC_ACQUIRE, "agent");
;             asm volatile("s_waitcnt vmcnt(0)" ::: "memory");
;         }
.LBB0_738:
	s_waitcnt vmcnt(0)
	v_mov_b32_e32 v0, v209
	s_waitcnt vmcnt(0) lgkmcnt(0)
	s_barrier
	s_nop 0
	v_cmp_eq_u32_e32 vcc, 0, v0
	s_and_saveexec_b64 s[4:5], vcc
	s_cbranch_execz .LBB0_790
	v_readlane_b32 s12, v255, 8
	v_readlane_b32 s13, v255, 9
	v_mov_b32_e32 v18, 0x20000
	ds_read2_b32 v[20:21], v18 offset1:1
	s_getreg_b32 s14, hwreg(HW_REG_XCC_ID, 0, 4)
	s_and_b32 s14, s14, 15
	s_mul_i32 s32, s56, 9
	s_add_i32 s32, s32, 6
	s_add_i32 s34, s32, 1
	v_mov_b32_e32 v19, 1
	v_mov_b32_e32 v22, 0
	s_waitcnt lgkmcnt(0)
	v_readfirstlane_b32 s24, v20
	v_readfirstlane_b32 s25, v21
	s_lshl_b32 s35, s14, 8
	s_add_u32 s70, s12, s35
	s_addc_u32 s71, s13, 0
	s_add_u32 s72, s70, 0x2400
	s_addc_u32 s73, s71, 0
	s_add_u32 s70, s70, 0x1400
	s_addc_u32 s71, s71, 0
	global_atomic_add v23, v22, v19, s[70:71] sc0
	s_mul_i32 s57, s34, s24
	s_waitcnt vmcnt(0)
	v_readfirstlane_b32 s44, v23
	s_nop 3
	s_add_i32 s44, s44, 1
	s_cmp_lg_u32 s44, s57
	s_cbranch_scc1 .Lfb7_spin
	buffer_wbl2 sc1
	s_waitcnt vmcnt(0)
	s_add_u32 s98, s12, 0x3400
	s_addc_u32 s99, s13, 0
	global_atomic_add v23, v22, v19, s[98:99] sc0
	s_mul_i32 s57, s34, s25
	s_waitcnt vmcnt(0)
	v_readfirstlane_b32 s44, v23
	s_nop 3
	s_add_i32 s44, s44, 1
	s_cmp_lg_u32 s44, s57
	s_cbranch_scc1 .Lfb7_spin
	global_atomic_add v22, v19, s[98:99] offset:256
	s_add_u32 s98, s12, 0x2400
	s_addc_u32 s99, s13, 0
	global_atomic_add v22, v19, s[98:99]
	global_atomic_add v22, v19, s[98:99] offset:256
	global_atomic_add v22, v19, s[98:99] offset:512
	global_atomic_add v22, v19, s[98:99] offset:768
	global_atomic_add v22, v19, s[98:99] offset:1024
	global_atomic_add v22, v19, s[98:99] offset:1280
	global_atomic_add v22, v19, s[98:99] offset:1536
	global_atomic_add v22, v19, s[98:99] offset:1792
	global_atomic_add v22, v19, s[98:99] offset:2048
	global_atomic_add v22, v19, s[98:99] offset:2304
	global_atomic_add v22, v19, s[98:99] offset:2560
	global_atomic_add v22, v19, s[98:99] offset:2816
	global_atomic_add v22, v19, s[98:99] offset:3072
	global_atomic_add v22, v19, s[98:99] offset:3328
	global_atomic_add v22, v19, s[98:99] offset:3584
	global_atomic_add v22, v19, s[98:99] offset:3840

; __device__ __forceinline__ int tid_() { int t = threadIdx.x; asm volatile("" : "+v"(t)); return t; }
; __device__ __forceinline__ int bid_() { int t = blockIdx.x; asm volatile("" : "+s"(t)); return t; }
; __device__ __forceinline__ void norm_phase(KP p, bool first, int nslab) {
;     const int tid = tid_(), lane = tid & 63, wave = __builtin_amdgcn_readfirstlane(tid >> 6);
;     const int gw = bid_() * 8 + wave, NGW = gdim_() * 8;
;     bf16_t* X = (bf16_t*)(p->ws + WS_X); bf16_t* XN = (bf16_t*)(p->ws + WS_R2);
;     const bool xaware = gdim_() == 256; const int cb = bid_(), xl = cb & 7, jl = cb >> 3;
;     for (int it = 0; it < 9; ++it) {
;         int m;
;         if (xaware) { if (it < 8) m = 2048 * xl + 256 * it + jl * 8 + wave; else { if (gw >= 256) break; m = 64 * 256 + gw; } }
;         else { m = gw + it * NGW; if (m >= M) break; }
;         f32x4 v[4]; float s = 0.f;
;         if (first) { const f32x4* xr = (const f32x4*)src_row(p, m) + lane;
; #pragma unroll
;             for (int j = 0; j < 4; ++j) v[j] = __builtin_nontemporal_load(xr + 64 * j); }
;         else { const u32x2* xr = (const u32x2*)(X + (size_t)m * D) + lane;
; #pragma unroll
;             for (int j = 0; j < 4; ++j) { const u32x2 w = __builtin_nontemporal_load(xr + 64 * j); v[j] = (f32x4){bflo(w.x), bfhi(w.x), bflo(w.y), bfhi(w.y)}; } }
;         const bool fold = (!first) && m >= 64 * 256;
;         if (fold) { const f32x4* sl = (const f32x4*)(p->ws + WS_SLAB) + (size_t)(m - 64 * 256) * (D / 4) + lane;
;             for (int q = 0; q < nslab; ++q) {
; #pragma unroll
;                 for (int j = 0; j < 4; ++j) v[j] += sl[(size_t)q * 256 * (D / 4) + 64 * j]; } }
;         if (first || fold) { u32x2* xo = (u32x2*)(X + (size_t)m * D) + lane;
; #pragma unroll
;             for (int j = 0; j < 4; ++j) { u32x2 w; w.x = cvt_pk_bf16(v[j][0], v[j][1]); w.y = cvt_pk_bf16(v[j][2], v[j][3]); xo[64 * j] = w; } }
; #pragma unroll
;         for (int j = 0; j < 4; ++j) s += (v[j][0] * v[j][0] + v[j][1] * v[j][1]) + (v[j][2] * v[j][2] + v[j][3] * v[j][3]);
;         const float rinv = rsqrtf(wave_sum(s) * (1.f / D) + EPS);
;         u32x2* o8 = (u32x2*)(XN + (size_t)m * D) + lane;
; #pragma unroll
;         for (int j = 0; j < 4; ++j) { u32x2 w; w.x = cvt_pk_bf16(v[j][0] * rinv, v[j][1] * rinv); w.y = cvt_pk_bf16(v[j][2] * rinv, v[j][3] * rinv); o8[64 * j] = w; }
.LBB0_790:
	s_or_b64 exec, exec, s[4:5]
	s_mov_b64 s[4:5], s[94:95]
	v_mov_b32_e32 v0, v209
	s_waitcnt lgkmcnt(0)
	s_barrier
	s_load_dwordx2 s[8:9], s[4:5], 0xe8
	v_and_b32_e32 v2, 63, v0
	v_readfirstlane_b32 s6, v0
	s_nop 3
	s_lshr_b32 s6, s6, 6
	s_waitcnt lgkmcnt(0)
	s_add_u32 s10, s8, 0x25c8000
	s_addc_u32 s11, s9, 0
	s_add_u32 s12, s8, 0x18c48000
	s_addc_u32 s13, s9, 0
	s_add_u32 s14, s8, 0x19068000
	s_addc_u32 s15, s9, 0
	s_cmpk_lt_u32 s2, 32
	s_cbranch_scc1 .Lnm_part2_p7
	s_cmpk_lt_u32 s2, 0xe0
	s_cbranch_scc1 .LBB0_807
	s_sub_i32 s16, s2, 0xe0
	s_lshl_b32 s16, s16, 3
	s_add_i32 s16, s16, s6
	s_add_i32 s18, s16, 0x4000
	s_lshl_b32 s19, s18, 2
	s_lshl_b32 s18, s18, 11
	s_add_u32 s10, s10, s18
	s_addc_u32 s11, s11, 0
	s_add_u32 s14, s14, s19
	s_addc_u32 s15, s15, 0
	v_lshlrev_b32_e32 v5, 3, v2
	v_lshlrev_b32_e32 v6, 4, v2
	global_load_dwordx2 v[18:19], v5, s[10:11]
	global_load_dwordx2 v[20:21], v5, s[10:11] offset:512
	global_load_dwordx2 v[22:23], v5, s[10:11] offset:1024
	global_load_dwordx2 v[24:25], v5, s[10:11] offset:1536
	s_lshl_b32 s18, s16, 12
	s_add_u32 s18, s8, s18
	s_addc_u32 s19, s9, 0
	s_add_u32 s18, s18, 0x1a3ac000
	s_addc_u32 s19, s19, 0
	global_load_dwordx4 v[32:35], v6, s[18:19]
	global_load_dwordx4 v[36:39], v6, s[18:19] offset:1024
	global_load_dwordx4 v[40:43], v6, s[18:19] offset:2048
	global_load_dwordx4 v[44:47], v6, s[18:19] offset:3072
	s_add_u32 s18, s18, 0x100000
	s_addc_u32 s19, s19, 0
	global_load_dwordx4 v[48:51], v6, s[18:19]
	global_load_dwordx4 v[52:55], v6, s[18:19] offset:1024
	global_load_dwordx4 v[56:59], v6, s[18:19] offset:2048
	global_load_dwordx4 v[60:63], v6, s[18:19] offset:3072
	s_add_u32 s18, s18, 0x100000
	s_addc_u32 s19, s19, 0
	global_load_dwordx4 v[64:67], v6, s[18:19]
	global_load_dwordx4 v[68:71], v6, s[18:19] offset:1024
	global_load_dwordx4 v[72:75], v6, s[18:19] offset:2048
	global_load_dwordx4 v[76:79], v6, s[18:19] offset:3072
	s_add_u32 s18, s18, 0x100000
	s_addc_u32 s19, s19, 0
	global_load_dwordx4 v[80:83], v6, s[18:19]
	global_load_dwordx4 v[84:87], v6, s[18:19] offset:1024
	global_load_dwordx4 v[88:91], v6, s[18:19] offset:2048
	global_load_dwordx4 v[92:95], v6, s[18:19] offset:3072
	s_add_u32 s18, s18, 0x100000
	s_addc_u32 s19, s19, 0
	s_waitcnt vmcnt(16)
	v_lshlrev_b32_e32 v224, 16, v18
	v_and_b32_e32 v225, 0xffff0000, v18
	v_lshlrev_b32_e32 v226, 16, v19
	v_and_b32_e32 v227, 0xffff0000, v19
	v_lshlrev_b32_e32 v228, 16, v20
	v_and_b32_e32 v229, 0xffff0000, v20
	v_lshlrev_b32_e32 v230, 16, v21
	v_and_b32_e32 v231, 0xffff0000, v21
	v_lshlrev_b32_e32 v232, 16, v22
	v_and_b32_e32 v233, 0xffff0000, v22
	v_lshlrev_b32_e32 v234, 16, v23
	v_and_b32_e32 v235, 0xffff0000, v23
	v_lshlrev_b32_e32 v236, 16, v24
	v_and_b32_e32 v237, 0xffff0000, v24
	v_lshlrev_b32_e32 v238, 16, v25
	v_and_b32_e32 v239, 0xffff0000, v25
	s_waitcnt vmcnt(12)
	v_add_f32_e32 v224, v224, v32
	v_add_f32_e32 v225, v225, v33
	v_add_f32_e32 v226, v226, v34
	v_add_f32_e32 v227, v227, v35
	v_add_f32_e32 v228, v228, v36
	v_add_f32_e32 v229, v229, v37
	v_add_f32_e32 v230, v230, v38
	v_add_f32_e32 v231, v231, v39
	v_add_f32_e32 v232, v232, v40
	v_add_f32_e32 v233, v233, v41
	v_add_f32_e32 v234, v234, v42
	v_add_f32_e32 v235, v235, v43
	v_add_f32_e32 v236, v236, v44
	v_add_f32_e32 v237, v237, v45
	v_add_f32_e32 v238, v238, v46
	v_add_f32_e32 v239, v239, v47
	s_waitcnt vmcnt(8)
	v_add_f32_e32 v224, v224, v48
	v_add_f32_e32 v225, v225, v49
	v_add_f32_e32 v226, v226, v50
	v_add_f32_e32 v227, v227, v51
	v_add_f32_e32 v228, v228, v52
	v_add_f32_e32 v229, v229, v53
	v_add_f32_e32 v230, v230, v54
	v_add_f32_e32 v231, v231, v55
	v_add_f32_e32 v232, v232, v56
	v_add_f32_e32 v233, v233, v57
	v_add_f32_e32 v234, v234, v58
	v_add_f32_e32 v235, v235, v59
	v_add_f32_e32 v236, v236, v60
	v_add_f32_e32 v237, v237, v61
	v_add_f32_e32 v238, v238, v62
	v_add_f32_e32 v239, v239, v63
	s_waitcnt vmcnt(4)
	v_add_f32_e32 v224, v224, v64
	v_add_f32_e32 v225, v225, v65
	v_add_f32_e32 v226, v226, v66
	v_add_f32_e32 v227, v227, v67
	v_add_f32_e32 v228, v228, v68
	v_add_f32_e32 v229, v229, v69
	v_add_f32_e32 v230, v230, v70
	v_add_f32_e32 v231, v231, v71
	v_add_f32_e32 v232, v232, v72
	v_add_f32_e32 v233, v233, v73
	v_add_f32_e32 v234, v234, v74
	v_add_f32_e32 v235, v235, v75
	v_add_f32_e32 v236, v236, v76
	v_add_f32_e32 v237, v237, v77
	v_add_f32_e32 v238, v238, v78
	v_add_f32_e32 v239, v239, v79
	s_waitcnt vmcnt(0)
	v_add_f32_e32 v224, v224, v80
	v_add_f32_e32 v225, v225, v81
	v_add_f32_e32 v226, v226, v82
	v_add_f32_e32 v227, v227, v83
	v_add_f32_e32 v228, v228, v84
	v_add_f32_e32 v229, v229, v85
	v_add_f32_e32 v230, v230, v86
	v_add_f32_e32 v231, v231, v87
	v_add_f32_e32 v232, v232, v88
	v_add_f32_e32 v233, v233, v89
	v_add_f32_e32 v234, v234, v90
	v_add_f32_e32 v235, v235, v91
	v_add_f32_e32 v236, v236, v92
	v_add_f32_e32 v237, v237, v93
	v_add_f32_e32 v238, v238, v94
	v_add_f32_e32 v239, v239, v95
	v_cvt_pk_bf16_f32 v26, v224, v225
	v_cvt_pk_bf16_f32 v27, v226, v227
	global_store_dwordx2 v5, v[26:27], s[10:11] sc0 sc1
	v_cvt_pk_bf16_f32 v28, v228, v229
	v_cvt_pk_bf16_f32 v29, v230, v231
	global_store_dwordx2 v5, v[28:29], s[10:11] offset:512 sc0 sc1
	v_cvt_pk_bf16_f32 v30, v232, v233
	v_cvt_pk_bf16_f32 v31, v234, v235
	global_store_dwordx2 v5, v[30:31], s[10:11] offset:1024 sc0 sc1
	v_cvt_pk_bf16_f32 v32, v236, v237
	v_cvt_pk_bf16_f32 v33, v238, v239
	global_store_dwordx2 v5, v[32:33], s[10:11] offset:1536 sc0 sc1
	v_mul_f32_e32 v7, v224, v224
	v_fmac_f32_e32 v7, v225, v225
	v_fmac_f32_e32 v7, v226, v226
	v_fmac_f32_e32 v7, v227, v227
	v_fmac_f32_e32 v7, v228, v228
	v_fmac_f32_e32 v7, v229, v229
	v_fmac_f32_e32 v7, v230, v230
	v_fmac_f32_e32 v7, v231, v231
	v_fmac_f32_e32 v7, v232, v232
	v_fmac_f32_e32 v7, v233, v233
	v_fmac_f32_e32 v7, v234, v234
	v_fmac_f32_e32 v7, v235, v235
	v_fmac_f32_e32 v7, v236, v236
	v_fmac_f32_e32 v7, v237, v237
	v_fmac_f32_e32 v7, v238, v238
	v_fmac_f32_e32 v7, v239, v239
	v_xor_b32_e32 v10, 1, v2
	v_lshlrev_b32_e32 v10, 2, v10
	ds_bpermute_b32 v10, v10, v7
	s_waitcnt lgkmcnt(0)
	v_add_f32_e32 v7, v7, v10
	v_xor_b32_e32 v10, 2, v2
	v_lshlrev_b32_e32 v10, 2, v10
	ds_bpermute_b32 v10, v10, v7
	s_waitcnt lgkmcnt(0)
	v_add_f32_e32 v7, v7, v10
	v_xor_b32_e32 v10, 4, v2
	v_lshlrev_b32_e32 v10, 2, v10
	ds_bpermute_b32 v10, v10, v7
	s_waitcnt lgkmcnt(0)
	v_add_f32_e32 v7, v7, v10
	v_xor_b32_e32 v10, 8, v2
	v_lshlrev_b32_e32 v10, 2, v10
	ds_bpermute_b32 v10, v10, v7
	s_waitcnt lgkmcnt(0)
	v_add_f32_e32 v7, v7, v10
	v_xor_b32_e32 v10, 16, v2
	v_lshlrev_b32_e32 v10, 2, v10
	ds_bpermute_b32 v10, v10, v7
	s_waitcnt lgkmcnt(0)
	v_add_f32_e32 v7, v7, v10
	v_xor_b32_e32 v10, 32, v2
	v_lshlrev_b32_e32 v10, 2, v10
	ds_bpermute_b32 v10, v10, v7
	s_waitcnt lgkmcnt(0)
	v_add_f32_e32 v7, v7, v10
	v_fmamk_f32 v7, v7, 0x3a800000, v213
	v_rsq_f32_e32 v7, v7
	s_nop 0
	global_store_dword v1, v7, s[14:15] sc0 sc1
	s_branch .LBB0_807

; #define LAS __attribute__((address_space(3)))
; __device__ __forceinline__ KP kargs() { KP k = (KP)__builtin_amdgcn_kernarg_segment_ptr(); asm volatile("" : "+s"(k)); return k; }
; __device__ __forceinline__ int tid_() { int t = threadIdx.x; asm volatile("" : "+v"(t)); return t; }
; __device__ __forceinline__ unsigned xb_ld(unsigned* p)              { return __hip_atomic_load(p, __ATOMIC_RELAXED, __HIP_MEMORY_SCOPE_AGENT); }
; __device__ __forceinline__ unsigned xb_add(unsigned* p, unsigned v) { return __hip_atomic_fetch_add(p, v, __ATOMIC_RELAXED, __HIP_MEMORY_SCOPE_AGENT); }
; __device__ __forceinline__ unsigned xb_xcc_id() { return (unsigned)__builtin_amdgcn_s_getreg((3 << 11) | 20) & 0xFu; }
; __device__ __forceinline__ void grid_barrier(LAS unsigned char* lds) {
;     asm volatile("s_waitcnt vmcnt(0)" ::: "memory");
;     __syncthreads();
;     if (tid_() == 0) {
;         unsigned* bar = (unsigned*)(kargs()->ws + WS_BAR);
;         volatile LAS unsigned* st = (volatile LAS unsigned*)(lds + LDS_BAR_OFF);
;         const unsigned x = xb_xcc_id();
;         __builtin_amdgcn_s_waitcnt(0);
;         unsigned nloc = st[0], nx = st[1];
;         if (nloc == 0u) { xcd_barrier_complete(bar, x, nloc, nx); st[0] = nloc; st[1] = nx; }
;         const unsigned old = xb_add(&bar[XB_XSUB(x)], 1u);
;         const unsigned gen = old / nloc;
;         if (old + 1u == (gen + 1u) * nloc) {
;             __builtin_amdgcn_fence(__ATOMIC_RELEASE, "agent");
;             asm volatile("s_waitcnt vmcnt(0)" ::: "memory");
;             const unsigned og = xb_add(&bar[XB_TOP], 1u);
;             const unsigned tg = og / nx;
;             if (og + 1u == (tg + 1u) * nx) xb_add(&bar[XB_TOPGEN], 1u);
;             else XB_SPIN(xb_ld(&bar[XB_TOPGEN]) == tg, bar);
;             __builtin_amdgcn_fence(__ATOMIC_ACQUIRE, "agent");
;             xb_add(&bar[XB_XGEN(x)], 1u);
;             asm volatile("s_waitcnt vmcnt(0)" ::: "memory");
;         } else {
;             XB_SPIN(xb_ld(&bar[XB_XGEN(x)]) == gen, bar);
;             __builtin_amdgcn_fence(__ATOMIC_ACQUIRE, "agent");
;             asm volatile("s_waitcnt vmcnt(0)" ::: "memory");
;         }
;     }
;     __syncthreads();
; }
; __global__ void __launch_bounds__(512, 2) fwd_megakernel(Params pv) {
;     ...
;         norm_phase(kargs(), false, 4);
;         grid_barrier(lds);
.LBB0_807:
	s_waitcnt vmcnt(0)
	v_mov_b32_e32 v0, v209
	s_barrier
	s_nop 0
	v_cmp_eq_u32_e32 vcc, 0, v0
	s_and_saveexec_b64 s[4:5], vcc
	s_cbranch_execz .LBB0_859
	v_readlane_b32 s12, v255, 8
	v_readlane_b32 s13, v255, 9
	v_mov_b32_e32 v19, 1
	v_mov_b32_e32 v22, 0
	s_lshl_b32 s35, s56, 3
	s_add_i32 s35, s35, 15876
	s_add_u32 s12, s12, s35
	s_addc_u32 s13, s13, 0
	global_atomic_add v22, v19, s[12:13]
	s_waitcnt vmcnt(0)

; __device__ __forceinline__ float dpp_ror1(float x) { return __builtin_bit_cast(float, __builtin_amdgcn_update_dpp(0, __builtin_bit_cast(int, x), 0x121, 0xf, 0xf, false)); }
; __device__ __forceinline__ float dpp_ror2(float x) { return __builtin_bit_cast(float, __builtin_amdgcn_update_dpp(0, __builtin_bit_cast(int, x), 0x122, 0xf, 0xf, false)); }
;     __device__ __forceinline__ void operator()(const f32x4 (&acc)[2][2][4][2], const Unit& u, int wr, int wc, int fr, int fq) const {
;         const int ch0 = u.pn * 128 + wc * 32 + 8 * fq;
;         float w0[8], w1[8], w2[8], bb[8]; load8f(cw + ch0, w0); load8f(cw + DFF + ch0, w1); load8f(cw + 2 * DFF + ch0, w2); load8f(cb + ch0, bb);
;         const int rbase = u.pm * BM + wr * 64 + fr;
;         const int b0 = (u.pm * BM) / TP, rb = (b0 + 1) * TP;
;     ...
;                 for (int m = 0; m < 4; ++m) { const int r = rbase + ai * HALF + 16 * m; const bool hi = r >= rb; const int t = hi ? r - rb : r - b0 * TP, b = hi ? b0 + 1 : b0;
;                     float o[8], uu[8], gg[8];
; #pragma unroll
;                     for (int k = 0; k < 8; ++k) { const float x = acc[ai][0][m][k >> 2][k & 3], g = acc[ai][1][m][k >> 2][k & 3]; uu[k] = x; gg[k] = g;
;                         float u1 = dpp_ror1(x), u2 = dpp_ror2(x);
;                         if (m > 0) { const float xp = acc[ai][0][m > 0 ? m - 1 : 0][k >> 2][k & 3]; const float p1 = dpp_ror1(xp), p2 = dpp_ror2(xp); u1 = fr >= 1 ? u1 : p1; u2 = fr >= 2 ? u2 : p2; }
.LBB0_883:
	v_lshl_or_b32 v174, s10, 7, v181
	v_lshlrev_b32_e32 v176, 2, v174
	s_lshl_b32 s91, s90, 8
	global_load_dwordx4 v[50:53], v176, s[66:67]
	global_load_dwordx4 v[54:57], v176, s[66:67] offset:16
	global_load_dwordx4 v[58:61], v176, s[78:79]
	global_load_dwordx4 v[62:65], v176, s[78:79] offset:16
	global_load_dwordx4 v[66:69], v176, s[80:81]
	global_load_dwordx4 v[70:73], v176, s[80:81] offset:16
	global_load_dwordx4 v[74:77], v176, s[68:69]
	global_load_dwordx4 v[78:81], v176, s[68:69] offset:16
	s_mul_hi_u32 s35, s91, 0xfe03f81
	s_lshr_b32 s35, s35, 7
	s_add_i32 s54, s35, 1
	s_mul_i32 s85, s54, 0x810
	s_add_i32 s91, s91, s18
	v_mul_u32_u24_e32 v183, s22, v178
	v_lshl_add_u32 v183, v174, 1, v183
	v_mul_u32_u24_e32 v236, s39, v178
	v_lshl_add_u32 v236, v174, 1, v236
	v_add_u32_e32 v237, s22, v236
	v_mul_i32_i24_e32 v238, s22, v180
	v_lshl_add_u32 v238, v174, 1, v238
	v_mul_i32_i24_e32 v239, s39, v180
	v_lshl_add_u32 v239, v174, 2, v239
	v_mul_u32_u24_e32 v248, 0x5800, v178
	v_lshl_add_u32 v248, v174, 2, v248
	s_cmp_lg_u32 s21, 0
	s_cbranch_scc1 .Lfw_p8_done
	s_lshl_b32 s10, s56, 3
	s_add_u32 s94, s60, 0x13ce3e04
	s_addc_u32 s95, s61, 0
	s_add_u32 s94, s94, s10
	s_addc_u32 s95, s95, 0
	v_mov_b32_e32 v249, 0
	s_mov_b32 s10, 0
.Lfw_p8_loop:
	global_load_dword v250, v249, s[94:95] sc0 sc1
	s_waitcnt vmcnt(0)
	v_readfirstlane_b32 s11, v250
	s_nop 3
	s_cmpk_ge_u32 s11, 0x100
	s_cbranch_scc1 .Lfw_p8_done
	s_sleep 1
	s_add_i32 s10, s10, 1
	s_cmp_lt_u32 s10, 0x100000
	s_cbranch_scc1 .Lfw_p8_loop
.Lfw_p8_done:
	s_add_u32 s94, s60, 0x129a0000
	s_addc_u32 s95, s61, 0
	s_lshl_b32 s10, s91, 2
	s_add_u32 s94, s94, s10
	s_addc_u32 s95, s95, 0
	v_lshlrev_b32_e32 v249, 2, v178
	global_load_dword v205, v249, s[94:95]
	global_load_dword v206, v249, s[94:95] offset:64
	global_load_dword v208, v249, s[94:95] offset:128
	global_load_dword v210, v249, s[94:95] offset:192
	global_load_dword v211, v249, s[94:95] offset:512
	global_load_dword v212, v249, s[94:95] offset:576
	global_load_dword v214, v249, s[94:95] offset:640
	global_load_dword v223, v249, s[94:95] offset:704
	s_waitcnt vmcnt(0)
	v_mul_f32_e32 v150, v205, v150
	v_mul_f32_e32 v151, v205, v151
	v_mul_f32_e32 v152, v205, v152
	v_mul_f32_e32 v153, v205, v153
	v_mul_f32_e32 v142, v205, v142
	v_mul_f32_e32 v143, v205, v143
	v_mul_f32_e32 v144, v205, v144
	v_mul_f32_e32 v145, v205, v145
	v_mul_f32_e32 v158, v205, v158
	v_mul_f32_e32 v159, v205, v159
	v_mul_f32_e32 v160, v205, v160
	v_mul_f32_e32 v161, v205, v161
	v_mul_f32_e32 v154, v205, v154
	v_mul_f32_e32 v155, v205, v155
	v_mul_f32_e32 v156, v205, v156
	v_mul_f32_e32 v157, v205, v157
	v_mul_f32_e32 v134, v206, v134
	v_mul_f32_e32 v135, v206, v135
	v_mul_f32_e32 v136, v206, v136
	v_mul_f32_e32 v137, v206, v137
	v_mul_f32_e32 v126, v206, v126
	v_mul_f32_e32 v127, v206, v127
	v_mul_f32_e32 v128, v206, v128
	v_mul_f32_e32 v129, v206, v129
	v_mul_f32_e32 v146, v206, v146
	v_mul_f32_e32 v147, v206, v147
	v_mul_f32_e32 v148, v206, v148
	v_mul_f32_e32 v149, v206, v149
	v_mul_f32_e32 v138, v206, v138
	v_mul_f32_e32 v139, v206, v139
	v_mul_f32_e32 v140, v206, v140
	v_mul_f32_e32 v141, v206, v141
	v_mul_f32_e32 v118, v208, v118
	v_mul_f32_e32 v119, v208, v119
	v_mul_f32_e32 v120, v208, v120
	v_mul_f32_e32 v121, v208, v121
	v_mul_f32_e32 v110, v208, v110
	v_mul_f32_e32 v111, v208, v111
	v_mul_f32_e32 v112, v208, v112
	v_mul_f32_e32 v113, v208, v113
	v_mul_f32_e32 v130, v208, v130
	v_mul_f32_e32 v131, v208, v131
	v_mul_f32_e32 v132, v208, v132
	v_mul_f32_e32 v133, v208, v133
	v_mul_f32_e32 v122, v208, v122
	v_mul_f32_e32 v123, v208, v123
	v_mul_f32_e32 v124, v208, v124
	v_mul_f32_e32 v125, v208, v125
	v_mul_f32_e32 v102, v210, v102
	v_mul_f32_e32 v103, v210, v103
	v_mul_f32_e32 v104, v210, v104
	v_mul_f32_e32 v105, v210, v105
	v_mul_f32_e32 v98, v210, v98
	v_mul_f32_e32 v99, v210, v99
	v_mul_f32_e32 v100, v210, v100
	v_mul_f32_e32 v101, v210, v101
	v_mul_f32_e32 v114, v210, v114
	v_mul_f32_e32 v115, v210, v115
	v_mul_f32_e32 v116, v210, v116
	v_mul_f32_e32 v117, v210, v117
	v_mul_f32_e32 v106, v210, v106
	v_mul_f32_e32 v107, v210, v107
	v_mul_f32_e32 v108, v210, v108
	v_mul_f32_e32 v109, v210, v109
	v_mul_f32_e32 v90, v211, v90
	v_mul_f32_e32 v91, v211, v91
	v_mul_f32_e32 v92, v211, v92
	v_mul_f32_e32 v93, v211, v93
	v_mul_f32_e32 v86, v211, v86
	v_mul_f32_e32 v87, v211, v87
	v_mul_f32_e32 v88, v211, v88
	v_mul_f32_e32 v89, v211, v89
	v_mul_f32_e32 v94, v211, v94
	v_mul_f32_e32 v95, v211, v95
	v_mul_f32_e32 v96, v211, v96
	v_mul_f32_e32 v97, v211, v97
	v_mul_f32_e32 v82, v211, v82
	v_mul_f32_e32 v83, v211, v83
	v_mul_f32_e32 v84, v211, v84
	v_mul_f32_e32 v85, v211, v85
	v_mul_f32_e32 v42, v212, v42
	v_mul_f32_e32 v43, v212, v43
	v_mul_f32_e32 v44, v212, v44
	v_mul_f32_e32 v45, v212, v45
	v_mul_f32_e32 v38, v212, v38
	v_mul_f32_e32 v39, v212, v39
	v_mul_f32_e32 v40, v212, v40
	v_mul_f32_e32 v41, v212, v41
	v_mul_f32_e32 v46, v212, v46
	v_mul_f32_e32 v47, v212, v47
	v_mul_f32_e32 v48, v212, v48
	v_mul_f32_e32 v49, v212, v49
	v_mul_f32_e32 v34, v212, v34
	v_mul_f32_e32 v35, v212, v35
; __device__ __forceinline__ u32x4 pack8(const float (&f)[8]) { u32x4 o; o.x = cvt_pk_bf16(f[0], f[1]); o.y = cvt_pk_bf16(f[2], f[3]); o.z = cvt_pk_bf16(f[4], f[5]); o.w = cvt_pk_bf16(f[6], f[7]); return o; }
; __device__ __forceinline__ float sigmoidf_(float x) { return __builtin_amdgcn_rcpf(1.0f + __expf(-x)); }
; __device__ __forceinline__ float dpp_ror1(float x) { return __builtin_bit_cast(float, __builtin_amdgcn_update_dpp(0, __builtin_bit_cast(int, x), 0x121, 0xf, 0xf, false)); }
; __device__ __forceinline__ float dpp_ror2(float x) { return __builtin_bit_cast(float, __builtin_amdgcn_update_dpp(0, __builtin_bit_cast(int, x), 0x122, 0xf, 0xf, false)); }
;     __device__ __forceinline__ void operator()(const f32x4 (&acc)[2][2][4][2], const Unit& u, int wr, int wc, int fr, int fq) const {
;     ...
;                 for (int m = 0; m < 4; ++m) { const int r = rbase + ai * HALF + 16 * m; const bool hi = r >= rb; const int t = hi ? r - rb : r - b0 * TP, b = hi ? b0 + 1 : b0;
;                     float o[8], uu[8], gg[8];
; #pragma unroll
;                     for (int k = 0; k < 8; ++k) { const float x = acc[ai][0][m][k >> 2][k & 3], g = acc[ai][1][m][k >> 2][k & 3]; uu[k] = x; gg[k] = g;
;                         float u1 = dpp_ror1(x), u2 = dpp_ror2(x);
;                         if (m > 0) { const float xp = acc[ai][0][m > 0 ? m - 1 : 0][k >> 2][k & 3]; const float p1 = dpp_ror1(xp), p2 = dpp_ror2(xp); u1 = fr >= 1 ? u1 : p1; u2 = fr >= 2 ? u2 : p2; }
;                         if (t == 0) u1 = 0.f; if (t <= 1) u2 = 0.f;
;                         const float uc = w0[k] * u2 + w1[k] * u1 + w2[k] * x + bb[k]; o[k] = uc * sigmoidf_(uc) * g; }
;                     if (m > 0 || fr >= 2) *(u32x4*)(ACT + (size_t)r * DFF + ch0) = pack8(o);
;                     if (m == 0 && fr < 2) { const int blk = r >> 6; *(u32x4*)(EF + ((size_t)(blk * 2 + fr) * 2) * DFF + ch0) = pack8(uu); *(u32x4*)(EF + ((size_t)(blk * 2 + fr) * 2 + 1) * DFF + ch0) = pack8(gg); }
;                     if (m == 3 && fr >= 14) { const int blk = r >> 6; *(u32x4*)(EL + (size_t)(blk * 2 + (fr - 14)) * DFF + ch0) = pack8(uu); }
;                     if (t >= TP - 2) store8f(outp + ((size_t)(b * 2) + (t - (TP - 2))) * DFF + ch0, uu); }
	v_mul_f32_e32 v36, v212, v36
	v_mul_f32_e32 v37, v212, v37
	v_mul_f32_e32 v26, v214, v26
	v_mul_f32_e32 v27, v214, v27
	v_mul_f32_e32 v28, v214, v28
	v_mul_f32_e32 v29, v214, v29
	v_mul_f32_e32 v22, v214, v22
	v_mul_f32_e32 v23, v214, v23
	v_mul_f32_e32 v24, v214, v24
	v_mul_f32_e32 v25, v214, v25
	v_mul_f32_e32 v30, v214, v30
	v_mul_f32_e32 v31, v214, v31
	v_mul_f32_e32 v32, v214, v32
	v_mul_f32_e32 v33, v214, v33
	v_mul_f32_e32 v18, v214, v18
	v_mul_f32_e32 v19, v214, v19
	v_mul_f32_e32 v20, v214, v20
	v_mul_f32_e32 v21, v214, v21
	v_mul_f32_e32 v10, v223, v10
	v_mul_f32_e32 v11, v223, v11
	v_mul_f32_e32 v12, v223, v12
	v_mul_f32_e32 v13, v223, v13
	v_mul_f32_e32 v6, v223, v6
	v_mul_f32_e32 v7, v223, v7
	v_mul_f32_e32 v8, v223, v8
	v_mul_f32_e32 v9, v223, v9
	v_mul_f32_e32 v14, v223, v14
	v_mul_f32_e32 v15, v223, v15
	v_mul_f32_e32 v16, v223, v16
	v_mul_f32_e32 v17, v223, v17
	v_mul_f32_e32 v2, v223, v2
	v_mul_f32_e32 v3, v223, v3
	v_mul_f32_e32 v4, v223, v4
	v_mul_f32_e32 v5, v223, v5
	s_add_i32 s55, s91, 0
	s_cmp_ge_i32 s55, s85
	s_cselect_b32 s83, s54, s35
	s_mul_i32 s32, s83, 0x810
	s_sub_i32 s32, s55, s32
	s_mul_i32 s10, s55, 0x1600
	s_add_u32 s92, s60, s10
	s_addc_u32 s93, s61, 0
	v_fma_f32 v184, v66, v150, v74
	v_fma_f32 v185, v67, v151, v75
	v_fma_f32 v186, v68, v152, v76
	v_fma_f32 v187, v69, v153, v77
	v_fma_f32 v188, v70, v142, v78
	v_fma_f32 v189, v71, v143, v79
	v_fma_f32 v190, v72, v144, v80
	v_fma_f32 v191, v73, v145, v81
	v_fmac_f32_dpp v184, v150, v58 row_shr:1 row_mask:0xf bank_mask:0xf
	v_fmac_f32_dpp v185, v151, v59 row_shr:1 row_mask:0xf bank_mask:0xf
	v_fmac_f32_dpp v186, v152, v60 row_shr:1 row_mask:0xf bank_mask:0xf
	v_fmac_f32_dpp v187, v153, v61 row_shr:1 row_mask:0xf bank_mask:0xf
	v_fmac_f32_dpp v188, v142, v62 row_shr:1 row_mask:0xf bank_mask:0xf
	v_fmac_f32_dpp v189, v143, v63 row_shr:1 row_mask:0xf bank_mask:0xf
	v_fmac_f32_dpp v190, v144, v64 row_shr:1 row_mask:0xf bank_mask:0xf
	v_fmac_f32_dpp v191, v145, v65 row_shr:1 row_mask:0xf bank_mask:0xf
	v_fmac_f32_dpp v184, v150, v50 row_shr:2 row_mask:0xf bank_mask:0xf
	v_fmac_f32_dpp v185, v151, v51 row_shr:2 row_mask:0xf bank_mask:0xf
	v_fmac_f32_dpp v186, v152, v52 row_shr:2 row_mask:0xf bank_mask:0xf
	v_fmac_f32_dpp v187, v153, v53 row_shr:2 row_mask:0xf bank_mask:0xf
	v_fmac_f32_dpp v188, v142, v54 row_shr:2 row_mask:0xf bank_mask:0xf
	v_fmac_f32_dpp v189, v143, v55 row_shr:2 row_mask:0xf bank_mask:0xf
	v_fmac_f32_dpp v190, v144, v56 row_shr:2 row_mask:0xf bank_mask:0xf
	v_fmac_f32_dpp v191, v145, v57 row_shr:2 row_mask:0xf bank_mask:0xf
	v_mul_f32_e32 v192, 0xbfb8aa3b, v184
	v_mul_f32_e32 v193, 0xbfb8aa3b, v185
	v_mul_f32_e32 v194, 0xbfb8aa3b, v186
	v_mul_f32_e32 v195, 0xbfb8aa3b, v187
	v_mul_f32_e32 v196, 0xbfb8aa3b, v188
	v_mul_f32_e32 v197, 0xbfb8aa3b, v189
	v_mul_f32_e32 v198, 0xbfb8aa3b, v190
	v_mul_f32_e32 v199, 0xbfb8aa3b, v191
	v_exp_f32_e32 v192, v192
	v_exp_f32_e32 v193, v193
	v_exp_f32_e32 v194, v194
	v_exp_f32_e32 v195, v195
	v_exp_f32_e32 v196, v196
	v_exp_f32_e32 v197, v197
	v_exp_f32_e32 v198, v198
	v_exp_f32_e32 v199, v199
	v_add_f32_e32 v192, 1.0, v192
	v_add_f32_e32 v193, 1.0, v193
	v_add_f32_e32 v194, 1.0, v194
	v_add_f32_e32 v195, 1.0, v195
	v_add_f32_e32 v196, 1.0, v196
	v_add_f32_e32 v197, 1.0, v197
	v_add_f32_e32 v198, 1.0, v198
	v_add_f32_e32 v199, 1.0, v199
	v_rcp_f32_e32 v192, v192
	v_rcp_f32_e32 v193, v193
	v_rcp_f32_e32 v194, v194
	v_rcp_f32_e32 v195, v195
	v_rcp_f32_e32 v196, v196
	v_rcp_f32_e32 v197, v197
	v_rcp_f32_e32 v198, v198
	v_rcp_f32_e32 v199, v199
	v_mul_f32_e32 v184, v184, v192
	v_mul_f32_e32 v185, v185, v193
	v_mul_f32_e32 v186, v186, v194
	v_mul_f32_e32 v187, v187, v195
	v_mul_f32_e32 v188, v188, v196
	v_mul_f32_e32 v189, v189, v197
	v_mul_f32_e32 v190, v190, v198
	v_mul_f32_e32 v191, v191, v199
	v_mul_f32_e32 v184, v158, v184
	v_mul_f32_e32 v185, v159, v185
	v_mul_f32_e32 v186, v160, v186
	v_mul_f32_e32 v187, v161, v187
	v_mul_f32_e32 v188, v154, v188
	v_mul_f32_e32 v189, v155, v189
	v_mul_f32_e32 v190, v156, v190
	v_mul_f32_e32 v191, v157, v191
	v_cvt_pk_bf16_f32 v200, v184, v185
	v_cvt_pk_bf16_f32 v201, v186, v187
	v_cvt_pk_bf16_f32 v202, v188, v189
	v_cvt_pk_bf16_f32 v203, v190, v191
	s_lshr_b32 s10, s55, 6
	s_mul_i32 s10, s10, 0x5800
	s_add_u32 s94, s62, s10
	s_addc_u32 s95, s63, 0
	s_mov_b64 exec, s[4:5]
	global_store_dwordx4 v183, v[200:203], s[92:93]
	s_mov_b64 exec, s[6:7]
	v_cvt_pk_bf16_f32 v228, v150, v151
	v_cvt_pk_bf16_f32 v229, v152, v153
	v_cvt_pk_bf16_f32 v230, v142, v143
	v_cvt_pk_bf16_f32 v231, v144, v145
	v_cvt_pk_bf16_f32 v232, v158, v159
	v_cvt_pk_bf16_f32 v233, v160, v161
	v_cvt_pk_bf16_f32 v234, v154, v155
	v_cvt_pk_bf16_f32 v235, v156, v157
	global_store_dwordx4 v236, v[228:231], s[94:95]
	global_store_dwordx4 v237, v[232:235], s[94:95]
	s_mov_b64 exec, -1
	s_cmpk_lg_i32 s32, 0x800
	s_cbranch_scc1 .Lp8e_noout_00
	s_mul_i32 s10, s83, 0x5800
	s_add_u32 s94, s72, s10
	s_addc_u32 s95, s73, 0
	s_mov_b64 exec, s[8:9]
	global_store_dwordx4 v239, v[150:153], s[94:95]
	global_store_dwordx4 v239, v[142:145], s[94:95] offset:16
	s_mov_b64 exec, -1

; #define LAS __attribute__((address_space(3)))
; __device__ __forceinline__ KP kargs() { KP k = (KP)__builtin_amdgcn_kernarg_segment_ptr(); asm volatile("" : "+s"(k)); return k; }
; __device__ __forceinline__ int tid_() { int t = threadIdx.x; asm volatile("" : "+v"(t)); return t; }
; __device__ __forceinline__ unsigned xb_ld(unsigned* p)              { return __hip_atomic_load(p, __ATOMIC_RELAXED, __HIP_MEMORY_SCOPE_AGENT); }
; __device__ __forceinline__ unsigned xb_add(unsigned* p, unsigned v) { return __hip_atomic_fetch_add(p, v, __ATOMIC_RELAXED, __HIP_MEMORY_SCOPE_AGENT); }
; __device__ __forceinline__ unsigned xb_xcc_id() { return (unsigned)__builtin_amdgcn_s_getreg((3 << 11) | 20) & 0xFu; }
; __device__ __forceinline__ void grid_barrier(LAS unsigned char* lds) {
;     asm volatile("s_waitcnt vmcnt(0)" ::: "memory");
;     __syncthreads();
;     if (tid_() == 0) {
;         unsigned* bar = (unsigned*)(kargs()->ws + WS_BAR);
;         volatile LAS unsigned* st = (volatile LAS unsigned*)(lds + LDS_BAR_OFF);
;         const unsigned x = xb_xcc_id();
;         __builtin_amdgcn_s_waitcnt(0);
;         unsigned nloc = st[0], nx = st[1];
;         if (nloc == 0u) { xcd_barrier_complete(bar, x, nloc, nx); st[0] = nloc; st[1] = nx; }
;         const unsigned old = xb_add(&bar[XB_XSUB(x)], 1u);
;         const unsigned gen = old / nloc;
;         if (old + 1u == (gen + 1u) * nloc) {
;             __builtin_amdgcn_fence(__ATOMIC_RELEASE, "agent");
;             asm volatile("s_waitcnt vmcnt(0)" ::: "memory");
;             const unsigned og = xb_add(&bar[XB_TOP], 1u);
;             const unsigned tg = og / nx;
;             if (og + 1u == (tg + 1u) * nx) xb_add(&bar[XB_TOPGEN], 1u);
;             else XB_SPIN(xb_ld(&bar[XB_TOPGEN]) == tg, bar);
;             __builtin_amdgcn_fence(__ATOMIC_ACQUIRE, "agent");
;             xb_add(&bar[XB_XGEN(x)], 1u);
;             asm volatile("s_waitcnt vmcnt(0)" ::: "memory");
;         } else {
;             XB_SPIN(xb_ld(&bar[XB_XGEN(x)]) == gen, bar);
;             __builtin_amdgcn_fence(__ATOMIC_ACQUIRE, "agent");
;             asm volatile("s_waitcnt vmcnt(0)" ::: "memory");
;         }
;     }
;     __syncthreads();
; }
; __global__ void __launch_bounds__(512, 2) fwd_megakernel(Params pv) {
;     ...
;         grid_barrier(lds);
.LBB0_956:
	s_waitcnt vmcnt(0)
	v_mov_b32_e32 v0, v209
	s_waitcnt lgkmcnt(0)
	s_barrier
	s_nop 0
	v_cmp_eq_u32_e32 vcc, 0, v0
	s_and_saveexec_b64 s[4:5], vcc
	v_readlane_b32 s0, v255, 1
	s_mov_b32 s90, 0x62000
	s_mov_b32 s94, 0x69000
	s_mov_b32 s95, 0x70000
	s_mov_b32 s20, 0x77000
	v_readlane_b32 s1, v255, 2
	s_mov_b32 s96, 0x8c000
	s_mov_b32 s21, 0xfe03f81
	s_cbranch_execz .LBB0_1008
	v_readlane_b32 s12, v255, 8
	v_readlane_b32 s13, v255, 9
	v_mov_b32_e32 v18, 0x20000
	ds_read2_b32 v[20:21], v18 offset1:1
	s_getreg_b32 s14, hwreg(HW_REG_XCC_ID, 0, 4)
	s_and_b32 s14, s14, 15
	s_mul_i32 s32, s86, 9
	s_add_i32 s32, s32, -2
	s_add_i32 s34, s32, 1
	v_mov_b32_e32 v19, 1
	v_mov_b32_e32 v22, 0
	s_waitcnt lgkmcnt(0)
	v_readfirstlane_b32 s24, v20
	v_readfirstlane_b32 s25, v21
	s_lshl_b32 s35, s14, 8
	s_add_u32 s70, s12, s35
	s_addc_u32 s71, s13, 0
	s_add_u32 s72, s70, 0x2400
	s_addc_u32 s73, s71, 0
	s_add_u32 s70, s70, 0x1400
	s_addc_u32 s71, s71, 0
	global_atomic_add v23, v22, v19, s[70:71] sc0
	s_mul_i32 s57, s34, s24
	s_waitcnt vmcnt(0)
	v_readfirstlane_b32 s44, v23
	s_nop 3
	s_add_i32 s44, s44, 1
	s_cmp_lg_u32 s44, s57
	s_cbranch_scc1 .Lfb9_spin
	buffer_wbl2 sc1
	s_waitcnt vmcnt(0)
	s_add_u32 s98, s12, 0x3400
	s_addc_u32 s99, s13, 0
	global_atomic_add v23, v22, v19, s[98:99] sc0
	s_mul_i32 s57, s34, s25
	s_waitcnt vmcnt(0)
	v_readfirstlane_b32 s44, v23
	s_nop 3
	s_add_i32 s44, s44, 1
	s_cmp_lg_u32 s44, s57
	s_cbranch_scc1 .Lfb9_spin
	global_atomic_add v22, v19, s[98:99] offset:256
	s_add_u32 s98, s12, 0x2400
	s_addc_u32 s99, s13, 0
	global_atomic_add v22, v19, s[98:99]
	global_atomic_add v22, v19, s[98:99] offset:256
	global_atomic_add v22, v19, s[98:99] offset:512
	global_atomic_add v22, v19, s[98:99] offset:768
	global_atomic_add v22, v19, s[98:99] offset:1024
	global_atomic_add v22, v19, s[98:99] offset:1280
	global_atomic_add v22, v19, s[98:99] offset:1536
	global_atomic_add v22, v19, s[98:99] offset:1792
	global_atomic_add v22, v19, s[98:99] offset:2048
	global_atomic_add v22, v19, s[98:99] offset:2304
	global_atomic_add v22, v19, s[98:99] offset:2560
	global_atomic_add v22, v19, s[98:99] offset:2816
	global_atomic_add v22, v19, s[98:99] offset:3072
	global_atomic_add v22, v19, s[98:99] offset:3328
	global_atomic_add v22, v19, s[98:99] offset:3584
	global_atomic_add v22, v19, s[98:99] offset:3840

; #define LAS __attribute__((address_space(3)))
; __device__ __forceinline__ KP kargs() { KP k = (KP)__builtin_amdgcn_kernarg_segment_ptr(); asm volatile("" : "+s"(k)); return k; }
; __device__ __forceinline__ int tid_() { int t = threadIdx.x; asm volatile("" : "+v"(t)); return t; }
; __device__ __forceinline__ unsigned xb_ld(unsigned* p)              { return __hip_atomic_load(p, __ATOMIC_RELAXED, __HIP_MEMORY_SCOPE_AGENT); }
; __device__ __forceinline__ unsigned xb_add(unsigned* p, unsigned v) { return __hip_atomic_fetch_add(p, v, __ATOMIC_RELAXED, __HIP_MEMORY_SCOPE_AGENT); }
; __device__ __forceinline__ unsigned xb_xcc_id() { return (unsigned)__builtin_amdgcn_s_getreg((3 << 11) | 20) & 0xFu; }
; __device__ __forceinline__ void grid_barrier(LAS unsigned char* lds) {
;     asm volatile("s_waitcnt vmcnt(0)" ::: "memory");
;     __syncthreads();
;     if (tid_() == 0) {
;         unsigned* bar = (unsigned*)(kargs()->ws + WS_BAR);
;         volatile LAS unsigned* st = (volatile LAS unsigned*)(lds + LDS_BAR_OFF);
;         const unsigned x = xb_xcc_id();
;         __builtin_amdgcn_s_waitcnt(0);
;         unsigned nloc = st[0], nx = st[1];
;         if (nloc == 0u) { xcd_barrier_complete(bar, x, nloc, nx); st[0] = nloc; st[1] = nx; }
;         const unsigned old = xb_add(&bar[XB_XSUB(x)], 1u);
;         const unsigned gen = old / nloc;
;         if (old + 1u == (gen + 1u) * nloc) {
;             __builtin_amdgcn_fence(__ATOMIC_RELEASE, "agent");
;             asm volatile("s_waitcnt vmcnt(0)" ::: "memory");
;             const unsigned og = xb_add(&bar[XB_TOP], 1u);
;             const unsigned tg = og / nx;
;             if (og + 1u == (tg + 1u) * nx) xb_add(&bar[XB_TOPGEN], 1u);
;             else XB_SPIN(xb_ld(&bar[XB_TOPGEN]) == tg, bar);
;             __builtin_amdgcn_fence(__ATOMIC_ACQUIRE, "agent");
;             xb_add(&bar[XB_XGEN(x)], 1u);
;             asm volatile("s_waitcnt vmcnt(0)" ::: "memory");
;         } else {
;             XB_SPIN(xb_ld(&bar[XB_XGEN(x)]) == gen, bar);
;             __builtin_amdgcn_fence(__ATOMIC_ACQUIRE, "agent");
;             asm volatile("s_waitcnt vmcnt(0)" ::: "memory");
;         }
;     }
;     __syncthreads();
; }
; __global__ void __launch_bounds__(512, 2) fwd_megakernel(Params pv) {
;     ...
;         grid_barrier(lds);
.LBB0_1015:
	s_or_b64 exec, exec, s[4:5]
	s_waitcnt vmcnt(0)
	v_mov_b32_e32 v0, v209
	s_barrier
	s_nop 0
	v_cmp_eq_u32_e32 vcc, 0, v0
	s_and_saveexec_b64 s[4:5], vcc
	s_mov_b32 s43, 0x54000
	s_mov_b32 s87, 0x5b000
	s_cbranch_execz .LBB0_1067
	v_readlane_b32 s12, v255, 8
	v_readlane_b32 s13, v255, 9
	v_mov_b32_e32 v18, 0x20000
	ds_read2_b32 v[20:21], v18 offset1:1
	s_getreg_b32 s14, hwreg(HW_REG_XCC_ID, 0, 4)
	s_and_b32 s14, s14, 15
	s_mul_i32 s32, s86, 9
	s_add_i32 s32, s32, -1
	s_add_i32 s34, s32, 1
	v_mov_b32_e32 v19, 1
	v_mov_b32_e32 v22, 0
	s_waitcnt lgkmcnt(0)
	v_readfirstlane_b32 s24, v20
	v_readfirstlane_b32 s25, v21
	s_lshl_b32 s35, s14, 8
	s_add_u32 s70, s12, s35
	s_addc_u32 s71, s13, 0
	s_add_u32 s72, s70, 0x2400
	s_addc_u32 s73, s71, 0
	s_add_u32 s70, s70, 0x1400
	s_addc_u32 s71, s71, 0
	global_atomic_add v23, v22, v19, s[70:71] sc0
	s_mul_i32 s57, s34, s24
	s_waitcnt vmcnt(0)
	v_readfirstlane_b32 s44, v23
	s_nop 3
	s_add_i32 s44, s44, 1
	s_cmp_lg_u32 s44, s57
	s_cbranch_scc1 .Lfb10_spin
	buffer_wbl2 sc1
	s_waitcnt vmcnt(0)
	s_add_u32 s98, s12, 0x3400
	s_addc_u32 s99, s13, 0
	global_atomic_add v23, v22, v19, s[98:99] sc0
	s_mul_i32 s57, s34, s25
	s_waitcnt vmcnt(0)
	v_readfirstlane_b32 s44, v23
	s_nop 3
	s_add_i32 s44, s44, 1
	s_cmp_lg_u32 s44, s57
	s_cbranch_scc1 .Lfb10_spin
	global_atomic_add v22, v19, s[98:99] offset:256
	s_add_u32 s98, s12, 0x2400
	s_addc_u32 s99, s13, 0
	global_atomic_add v22, v19, s[98:99]
	global_atomic_add v22, v19, s[98:99] offset:256
	global_atomic_add v22, v19, s[98:99] offset:512
	global_atomic_add v22, v19, s[98:99] offset:768
	global_atomic_add v22, v19, s[98:99] offset:1024
	global_atomic_add v22, v19, s[98:99] offset:1280
	global_atomic_add v22, v19, s[98:99] offset:1536
	global_atomic_add v22, v19, s[98:99] offset:1792
	global_atomic_add v22, v19, s[98:99] offset:2048
	global_atomic_add v22, v19, s[98:99] offset:2304
	global_atomic_add v22, v19, s[98:99] offset:2560
	global_atomic_add v22, v19, s[98:99] offset:2816
	global_atomic_add v22, v19, s[98:99] offset:3072
	global_atomic_add v22, v19, s[98:99] offset:3328
	global_atomic_add v22, v19, s[98:99] offset:3584
	global_atomic_add v22, v19, s[98:99] offset:3840

; #define LAS __attribute__((address_space(3)))
; __device__ __forceinline__ KP kargs() { KP k = (KP)__builtin_amdgcn_kernarg_segment_ptr(); asm volatile("" : "+s"(k)); return k; }
; __device__ __forceinline__ int tid_() { int t = threadIdx.x; asm volatile("" : "+v"(t)); return t; }
; __device__ __forceinline__ unsigned xb_ld(unsigned* p)              { return __hip_atomic_load(p, __ATOMIC_RELAXED, __HIP_MEMORY_SCOPE_AGENT); }
; __device__ __forceinline__ unsigned xb_add(unsigned* p, unsigned v) { return __hip_atomic_fetch_add(p, v, __ATOMIC_RELAXED, __HIP_MEMORY_SCOPE_AGENT); }
; __device__ __forceinline__ unsigned xb_xcc_id() { return (unsigned)__builtin_amdgcn_s_getreg((3 << 11) | 20) & 0xFu; }
; __device__ __forceinline__ void grid_barrier(LAS unsigned char* lds) {
;     asm volatile("s_waitcnt vmcnt(0)" ::: "memory");
;     __syncthreads();
;     if (tid_() == 0) {
;         unsigned* bar = (unsigned*)(kargs()->ws + WS_BAR);
;         volatile LAS unsigned* st = (volatile LAS unsigned*)(lds + LDS_BAR_OFF);
;         const unsigned x = xb_xcc_id();
;         __builtin_amdgcn_s_waitcnt(0);
;         unsigned nloc = st[0], nx = st[1];
;         if (nloc == 0u) { xcd_barrier_complete(bar, x, nloc, nx); st[0] = nloc; st[1] = nx; }
;         const unsigned old = xb_add(&bar[XB_XSUB(x)], 1u);
;         const unsigned gen = old / nloc;
;         if (old + 1u == (gen + 1u) * nloc) {
;             __builtin_amdgcn_fence(__ATOMIC_RELEASE, "agent");
;             asm volatile("s_waitcnt vmcnt(0)" ::: "memory");
;             const unsigned og = xb_add(&bar[XB_TOP], 1u);
;             const unsigned tg = og / nx;
;             if (og + 1u == (tg + 1u) * nx) xb_add(&bar[XB_TOPGEN], 1u);
;             else XB_SPIN(xb_ld(&bar[XB_TOPGEN]) == tg, bar);
;             __builtin_amdgcn_fence(__ATOMIC_ACQUIRE, "agent");
;             xb_add(&bar[XB_XGEN(x)], 1u);
;             asm volatile("s_waitcnt vmcnt(0)" ::: "memory");
;         } else {
;             XB_SPIN(xb_ld(&bar[XB_XGEN(x)]) == gen, bar);
;             __builtin_amdgcn_fence(__ATOMIC_ACQUIRE, "agent");
;             asm volatile("s_waitcnt vmcnt(0)" ::: "memory");
;         }
;     }
;     __syncthreads();
; }
; __global__ void __launch_bounds__(512, 2) fwd_megakernel(Params pv) {
;     ...
;         grid_barrier(lds);
.LBB0_1111:
	s_waitcnt vmcnt(0)
	v_mov_b32_e32 v0, v209
	s_waitcnt vmcnt(0) lgkmcnt(0)
	s_barrier
	s_nop 0
	v_cmp_eq_u32_e32 vcc, 0, v0
	s_and_saveexec_b64 s[4:5], vcc
	s_cbranch_execz .Lfb11_skip
	v_readlane_b32 s12, v255, 8
	v_readlane_b32 s13, v255, 9
	v_mov_b32_e32 v18, 0x20000
	ds_read2_b32 v[20:21], v18 offset1:1
	s_getreg_b32 s14, hwreg(HW_REG_XCC_ID, 0, 4)
	s_and_b32 s14, s14, 15
	s_mul_i32 s32, s86, 9
	s_add_i32 s32, s32, 0
	s_add_i32 s34, s32, 1
	v_mov_b32_e32 v19, 1
	v_mov_b32_e32 v22, 0
	s_waitcnt lgkmcnt(0)
	v_readfirstlane_b32 s24, v20
	v_readfirstlane_b32 s25, v21
	s_lshl_b32 s35, s14, 8
	s_add_u32 s70, s12, s35
	s_addc_u32 s71, s13, 0
	s_add_u32 s72, s70, 0x2400
	s_addc_u32 s73, s71, 0
	s_add_u32 s70, s70, 0x1400
	s_addc_u32 s71, s71, 0
	global_atomic_add v23, v22, v19, s[70:71] sc0
	s_mul_i32 s57, s34, s24
	s_waitcnt vmcnt(0)
	v_readfirstlane_b32 s44, v23
	s_nop 3
	s_add_i32 s44, s44, 1
	s_cmp_lg_u32 s44, s57
	s_cbranch_scc1 .Lfb11_spin
	buffer_wbl2 sc1
	s_waitcnt vmcnt(0)
	s_add_u32 s98, s12, 0x3400
	s_addc_u32 s99, s13, 0
	global_atomic_add v23, v22, v19, s[98:99] sc0
	s_mul_i32 s57, s34, s25
	s_waitcnt vmcnt(0)
	v_readfirstlane_b32 s44, v23
	s_nop 3
	s_add_i32 s44, s44, 1
	s_cmp_lg_u32 s44, s57
	s_cbranch_scc1 .Lfb11_spin
	global_atomic_add v22, v19, s[98:99] offset:256
	s_add_u32 s98, s12, 0x2400
	s_addc_u32 s99, s13, 0
	global_atomic_add v22, v19, s[98:99]
	global_atomic_add v22, v19, s[98:99] offset:256
	global_atomic_add v22, v19, s[98:99] offset:512
	global_atomic_add v22, v19, s[98:99] offset:768
	global_atomic_add v22, v19, s[98:99] offset:1024
	global_atomic_add v22, v19, s[98:99] offset:1280
	global_atomic_add v22, v19, s[98:99] offset:1536
	global_atomic_add v22, v19, s[98:99] offset:1792
	global_atomic_add v22, v19, s[98:99] offset:2048
	global_atomic_add v22, v19, s[98:99] offset:2304
	global_atomic_add v22, v19, s[98:99] offset:2560
	global_atomic_add v22, v19, s[98:99] offset:2816
	global_atomic_add v22, v19, s[98:99] offset:3072
	global_atomic_add v22, v19, s[98:99] offset:3328
	global_atomic_add v22, v19, s[98:99] offset:3584
	global_atomic_add v22, v19, s[98:99] offset:3840
